# lever 4: per-phase s_setprio flips removed from the GEMM K-loops, one static s_setprio 1 for the second wave half (wr=1) per GEMM phase
# speedup vs baseline: 1.0120x; 1.0109x over previous
.LBB0_70:
	s_or_b64 exec, exec, s[0:1]
	s_add_u32 s58, s50, 0x3800000
	s_addc_u32 s59, s51, 0
	s_add_u32 s56, s50, 0x7800000
	s_addc_u32 s57, s51, 0
	s_cmpk_lt_i32 s30, 0xc00
	s_waitcnt lgkmcnt(0)
	v_mov_b32_e32 v1, v188
	s_cselect_b64 s[0:1], -1, 0
	v_mov_b32_e32 v11, v188
	s_barrier
	s_ashr_i32 s88, s68, 31
	s_ashr_i32 s87, s30, 31
	v_writelane_b32 v253, s0, 1
	v_readfirstlane_b32 s3, v11
	s_and_b64 vcc, exec, s[0:1]
	v_writelane_b32 v253, s1, 2
	s_cbranch_vccz .LBB0_86
	v_lshlrev_b32_e32 v1, 4, v11
	v_add_u32_e32 v2, 0x2000, v1
	v_ashrrev_i32_e32 v3, 31, v2
	v_lshrrev_b32_e32 v3, 22, v3
	v_add_u32_e32 v3, v2, v3
	v_ashrrev_i32_e32 v10, 10, v3
	v_mul_i32_i24_e32 v3, 0x400, v10
	v_sub_u32_e32 v2, v2, v3
	v_lshrrev_b32_e32 v3, 4, v2
	v_bitop3_b32 v2, v3, v2, 32 bitop3:0x6c
	v_ashrrev_i32_e32 v3, 31, v2
	v_lshrrev_b32_e32 v3, 26, v3
	v_add_u32_e32 v3, v2, v3
	v_lshlrev_b32_e32 v4, 3, v10
	v_ashrrev_i32_e32 v12, 6, v3
	v_and_b32_e32 v4, -16, v4
	v_add_u32_e32 v4, v12, v4
	v_lshlrev_b32_e32 v5, 2, v4
	v_and_b32_e32 v6, 3, v12
	s_lshr_b32 s0, s87, 29
	v_and_or_b32 v5, v5, 48, v6
	v_lshlrev_b32_e32 v6, 1, v4
	v_lshrrev_b32_e32 v7, 2, v4
	v_and_b32_e32 v3, 0xc0, v3
	s_add_i32 s0, s30, s0
	s_ashr_i32 s6, s3, 6
	v_and_b32_e32 v6, 0xfffc0, v6
	v_and_b32_e32 v7, 4, v7
	v_sub_u32_e32 v2, v2, v3
	v_mov_b32_e32 v3, 1
	s_ashr_i32 s1, s0, 3
	s_and_b32 s0, s0, -8
	s_ashr_i32 s2, s3, 8
	s_lshl_b32 s35, s6, 10
	v_or3_b32 v5, v5, v6, v7
	v_lshlrev_b32_e32 v6, 5, v10
	v_ashrrev_i16_sdwa v2, v3, sext(v2) dst_sel:DWORD dst_unused:UNUSED_PAD src0_sel:DWORD src1_sel:BYTE_0
	s_sub_i32 s0, s30, s0
	v_and_b32_e32 v6, 32, v6
	v_bfe_i32 v13, v2, 0, 16
	s_cmp_lt_i32 s0, 0
	s_movk_i32 s72, 0x181
	v_add_lshl_u32 v2, v6, v13, 1
	s_cselect_b32 s4, s72, 0x180
	v_lshl_add_u32 v130, v5, 12, v2
	v_lshl_add_u32 v132, v4, 12, v2
	v_bfe_i32 v2, v11, 27, 1
	s_mul_i32 s0, s0, s4
	v_lshrrev_b32_e32 v2, 22, v2
	s_add_i32 s0, s0, s1
	v_add_u32_e32 v2, v1, v2
	s_mul_hi_i32 s1, s0, 0x2aaaaaab
	v_and_b32_e32 v2, 0xfffffc00, v2
	s_lshr_b32 s4, s1, 31
	s_ashr_i32 s1, s1, 6
	v_sub_u32_e32 v1, v1, v2
	s_add_i32 s1, s1, s4
	v_lshrrev_b32_e32 v2, 4, v1
	v_ashrrev_i32_e32 v4, 31, v11
	s_lshl_b32 s4, s1, 3
	s_mulk_i32 s1, 0x180
	v_bitop3_b32 v1, v2, v1, 32 bitop3:0x6c
	v_lshrrev_b32_e32 v4, 26, v4
	s_sub_i32 s1, s0, s1
	v_ashrrev_i32_e32 v2, 31, v1
	v_add_u32_e32 v4, v11, v4
	s_sext_i32_i16 s0, s1
	v_lshrrev_b32_e32 v2, 26, v2
	v_ashrrev_i32_e32 v15, 6, v4
	s_bfe_u32 s0, s0, 0x3001c
	v_add_u32_e32 v2, v1, v2
	v_lshlrev_b32_e32 v4, 3, v15
	s_add_i32 s5, s1, s0
	v_ashrrev_i32_e32 v14, 6, v2
	v_and_b32_e32 v4, -16, v4
	s_sext_i32_i16 s0, s5
	s_and_b32 s5, s5, 0xfff8
	v_add_u32_e32 v4, v14, v4
	s_sub_i32 s1, s1, s5
	v_lshlrev_b32_e32 v5, 2, v4
	v_and_b32_e32 v6, 3, v14
	s_sext_i32_i16 s1, s1
	v_and_or_b32 v5, v5, 48, v6
	v_lshlrev_b32_e32 v6, 1, v4
	v_lshrrev_b32_e32 v7, 2, v4
	v_and_b32_e32 v2, 0xc0, v2
	s_lshr_b32 s0, s0, 3
	s_add_i32 s16, s4, s1
	v_and_b32_e32 v6, 0xfffc0, v6
	v_and_b32_e32 v7, 4, v7
	v_sub_u32_e32 v1, v1, v2
	s_ashr_i32 s17, s16, 31
	s_bfe_i64 s[8:9], s[0:1], 0x100000
	v_or3_b32 v5, v5, v6, v7
	v_lshlrev_b32_e32 v6, 5, v15
	v_ashrrev_i16_sdwa v1, v3, sext(v1) dst_sel:DWORD dst_unused:UNUSED_PAD src0_sel:DWORD src1_sel:BYTE_0
	s_lshl_b64 s[4:5], s[16:17], 20
	s_lshl_b64 s[8:9], s[8:9], 20
	v_and_b32_e32 v6, 32, v6
	v_bfe_i32 v16, v1, 0, 16
	s_add_u32 s22, s70, s8
	v_add_lshl_u32 v1, v6, v16, 1
	s_addc_u32 s23, s71, s9
	s_add_i32 s17, s35, 0
	v_lshl_add_u32 v134, v5, 12, v1
	s_add_i32 m0, s17, 0x10000
	v_lshl_add_u32 v136, v4, 12, v1
	global_load_lds_dwordx4 v134, s[22:23]
	s_add_i32 m0, s17, 0x12000
	s_add_u32 s8, s22, 0x8000
	global_load_lds_dwordx4 v130, s[22:23]
	s_addc_u32 s9, s23, 0
	s_add_i32 m0, s17, 0x14000
	v_mov_b32_e32 v139, 0
	global_load_lds_dwordx4 v134, s[8:9]
	s_add_i32 m0, s17, 0x16000
	s_add_u32 s20, s58, s4
	s_addc_u32 s21, s59, s5
	s_add_i32 s73, s17, 0x2000
	global_load_lds_dwordx4 v130, s[8:9]
	s_mov_b32 m0, s17
	s_add_u32 s4, s20, 0x80000
	global_load_lds_dwordx4 v136, s[20:21]
	s_mov_b32 m0, s73
	s_addc_u32 s5, s21, 0
	s_add_i32 s74, s17, 0x4000
	global_load_lds_dwordx4 v132, s[20:21]
	s_mov_b32 m0, s74
	s_add_i32 s75, s17, 0x6000
	global_load_lds_dwordx4 v136, s[4:5]
	s_mov_b32 m0, s75
	v_mov_b32_e32 v135, v139
	global_load_lds_dwordx4 v132, s[4:5]
	v_mov_b32_e32 v131, v139
	v_mov_b32_e32 v137, v139
	v_mov_b32_e32 v133, v139
	s_cmp_eq_u32 s2, 1
	s_mov_b32 s1, 0
	v_lshl_add_u64 v[8:9], s[22:23], 0, v[134:135]
	v_lshl_add_u64 v[6:7], s[22:23], 0, v[130:131]
	v_lshl_add_u64 v[2:3], s[20:21], 0, v[136:137]
	s_cselect_b64 s[4:5], -1, 0
	s_cmp_lg_u32 s2, 1
	v_lshl_add_u64 v[4:5], s[20:21], 0, v[132:133]
	s_cbranch_scc1 .LBB0_73
	s_barrier
	s_setprio 1

.LBB0_79:
	ds_read_b128 v[154:157], v149
	ds_read_b128 v[158:161], v149 offset:1024
	ds_read_b128 v[162:165], v149 offset:2048
	ds_read_b128 v[166:169], v149 offset:3072
	ds_read_b128 v[170:173], v150
	ds_read_b128 v[174:177], v150 offset:1024
	ds_read_b128 v[178:181], v150 offset:2048
	ds_read_b128 v[182:185], v150 offset:3072
	s_add_u32 s22, s20, 0xfff80080
	s_addc_u32 s23, s21, -1
	s_cmp_eq_u32 s86, 28
	s_cselect_b32 s25, s13, s23
	s_cselect_b32 s24, s95, s22
	s_cselect_b32 s23, s11, vcc_lo
	s_cselect_b32 s22, s96, s97
	v_lshl_add_u64 v[186:187], s[20:21], 0, v[140:141]
	s_add_i32 m0, s17, 0xc000
	ds_read_b128 v[190:193], v151
	ds_read_b128 v[194:197], v151 offset:1024
	ds_read_b128 v[198:201], v151 offset:2048
	ds_read_b128 v[202:205], v151 offset:3072
	ds_read_b128 v[206:209], v151 offset:4096
	ds_read_b128 v[210:213], v151 offset:5120
	ds_read_b128 v[214:217], v151 offset:6144
	ds_read_b128 v[218:221], v151 offset:7168
	global_load_lds_dwordx4 v[186:187], off
	v_lshl_add_u64 v[186:187], s[20:21], 0, v[142:143]
	s_add_i32 m0, s17, 0xe000
	s_nop 0
	global_load_lds_dwordx4 v[186:187], off
	s_waitcnt vmcnt(8)
	s_waitcnt lgkmcnt(0)
	s_barrier
	s_waitcnt lgkmcnt(0)
	v_mfma_f32_16x16x32_bf16 v[126:129], v[154:157], v[190:193], v[126:129]
	v_mfma_f32_16x16x32_bf16 v[122:125], v[162:165], v[190:193], v[122:125]
	v_mfma_f32_16x16x32_bf16 v[118:121], v[154:157], v[198:201], v[118:121]
	v_mfma_f32_16x16x32_bf16 v[110:113], v[162:165], v[198:201], v[110:113]
	v_mfma_f32_16x16x32_bf16 v[98:101], v[154:157], v[206:209], v[98:101]
	v_mfma_f32_16x16x32_bf16 v[90:93], v[162:165], v[206:209], v[90:93]
	v_mfma_f32_16x16x32_bf16 v[82:85], v[154:157], v[214:217], v[82:85]
	v_mfma_f32_16x16x32_bf16 v[74:77], v[162:165], v[214:217], v[74:77]
	v_mfma_f32_16x16x32_bf16 v[126:129], v[158:161], v[194:197], v[126:129]
	v_mfma_f32_16x16x32_bf16 v[122:125], v[166:169], v[194:197], v[122:125]
	v_mfma_f32_16x16x32_bf16 v[118:121], v[158:161], v[202:205], v[118:121]
	v_mfma_f32_16x16x32_bf16 v[110:113], v[166:169], v[202:205], v[110:113]
	v_mfma_f32_16x16x32_bf16 v[98:101], v[158:161], v[210:213], v[98:101]
	v_mfma_f32_16x16x32_bf16 v[90:93], v[166:169], v[210:213], v[90:93]
	v_mfma_f32_16x16x32_bf16 v[82:85], v[158:161], v[218:221], v[82:85]
	v_mfma_f32_16x16x32_bf16 v[74:77], v[166:169], v[218:221], v[74:77]
	v_mfma_f32_16x16x32_bf16 v[114:117], v[170:173], v[190:193], v[114:117]
	v_mfma_f32_16x16x32_bf16 v[106:109], v[178:181], v[190:193], v[106:109]
	v_mfma_f32_16x16x32_bf16 v[102:105], v[170:173], v[198:201], v[102:105]
	v_mfma_f32_16x16x32_bf16 v[94:97], v[178:181], v[198:201], v[94:97]
	v_mfma_f32_16x16x32_bf16 v[86:89], v[170:173], v[206:209], v[86:89]
	v_mfma_f32_16x16x32_bf16 v[78:81], v[178:181], v[206:209], v[78:81]
	v_mfma_f32_16x16x32_bf16 v[70:73], v[170:173], v[214:217], v[70:73]
	v_mfma_f32_16x16x32_bf16 v[66:69], v[178:181], v[214:217], v[66:69]
	v_mfma_f32_16x16x32_bf16 v[114:117], v[174:177], v[194:197], v[114:117]
	v_mfma_f32_16x16x32_bf16 v[106:109], v[182:185], v[194:197], v[106:109]
	v_mfma_f32_16x16x32_bf16 v[102:105], v[174:177], v[202:205], v[102:105]
	v_mfma_f32_16x16x32_bf16 v[94:97], v[182:185], v[202:205], v[94:97]
	v_mfma_f32_16x16x32_bf16 v[86:89], v[174:177], v[210:213], v[86:89]
	v_mfma_f32_16x16x32_bf16 v[78:81], v[182:185], v[210:213], v[78:81]
	v_mfma_f32_16x16x32_bf16 v[70:73], v[174:177], v[218:221], v[70:73]
	v_mfma_f32_16x16x32_bf16 v[66:69], v[182:185], v[218:221], v[66:69]
	s_barrier
	s_add_i32 s26, s80, s35
	v_lshl_add_u64 v[186:187], s[22:23], 0, v[134:135]
	s_mov_b32 m0, s26
	ds_read_b128 v[190:193], v151 offset:16384
	ds_read_b128 v[194:197], v151 offset:17408
	ds_read_b128 v[198:201], v151 offset:18432
	ds_read_b128 v[202:205], v151 offset:19456
	ds_read_b128 v[206:209], v151 offset:20480
	ds_read_b128 v[210:213], v151 offset:21504
	ds_read_b128 v[214:217], v151 offset:22528
	ds_read_b128 v[218:221], v151 offset:23552
	global_load_lds_dwordx4 v[186:187], off
	s_add_i32 m0, s26, 0x2000
	s_add_u32 s26, s22, 0x8000
	v_lshl_add_u64 v[222:223], s[22:23], 0, v[130:131]
	s_addc_u32 s27, s23, 0
	s_add_i32 vcc_hi, s81, s35
	global_load_lds_dwordx4 v[222:223], off
	v_lshl_add_u64 v[224:225], s[26:27], 0, v[134:135]
	s_mov_b32 m0, vcc_hi
	v_lshl_add_u64 v[226:227], s[24:25], 0, v[132:133]
	global_load_lds_dwordx4 v[224:225], off
	v_lshl_add_u64 v[224:225], s[26:27], 0, v[130:131]
	s_add_i32 m0, vcc_hi, 0x2000
	s_nop 0
	global_load_lds_dwordx4 v[224:225], off
	v_lshl_add_u64 v[224:225], s[24:25], 0, v[136:137]
	s_mov_b32 m0, s17
	s_nop 0
	global_load_lds_dwordx4 v[224:225], off
	s_mov_b32 m0, s73
	s_nop 0
	global_load_lds_dwordx4 v[226:227], off
	s_waitcnt vmcnt(8)
	s_waitcnt lgkmcnt(0)
	s_barrier
	s_waitcnt lgkmcnt(0)
	v_mfma_f32_16x16x32_bf16 v[62:65], v[154:157], v[190:193], v[62:65]
	v_mfma_f32_16x16x32_bf16 v[58:61], v[162:165], v[190:193], v[58:61]
	v_mfma_f32_16x16x32_bf16 v[54:57], v[154:157], v[198:201], v[54:57]
	v_mfma_f32_16x16x32_bf16 v[46:49], v[162:165], v[198:201], v[46:49]
	v_mfma_f32_16x16x32_bf16 v[38:41], v[154:157], v[206:209], v[38:41]
	v_mfma_f32_16x16x32_bf16 v[30:33], v[162:165], v[206:209], v[30:33]
	v_mfma_f32_16x16x32_bf16 v[22:25], v[154:157], v[214:217], v[22:25]
	v_mfma_f32_16x16x32_bf16 v[14:17], v[162:165], v[214:217], v[14:17]
	v_mfma_f32_16x16x32_bf16 v[62:65], v[158:161], v[194:197], v[62:65]
	v_mfma_f32_16x16x32_bf16 v[58:61], v[166:169], v[194:197], v[58:61]
	v_mfma_f32_16x16x32_bf16 v[54:57], v[158:161], v[202:205], v[54:57]
	v_mfma_f32_16x16x32_bf16 v[46:49], v[166:169], v[202:205], v[46:49]
	v_mfma_f32_16x16x32_bf16 v[38:41], v[158:161], v[210:213], v[38:41]
	v_mfma_f32_16x16x32_bf16 v[30:33], v[166:169], v[210:213], v[30:33]
	v_mfma_f32_16x16x32_bf16 v[22:25], v[158:161], v[218:221], v[22:25]
	v_mfma_f32_16x16x32_bf16 v[14:17], v[166:169], v[218:221], v[14:17]
	v_mfma_f32_16x16x32_bf16 v[50:53], v[170:173], v[190:193], v[50:53]
	v_mfma_f32_16x16x32_bf16 v[42:45], v[178:181], v[190:193], v[42:45]
	v_mfma_f32_16x16x32_bf16 v[34:37], v[170:173], v[198:201], v[34:37]
	v_mfma_f32_16x16x32_bf16 v[26:29], v[178:181], v[198:201], v[26:29]
	v_mfma_f32_16x16x32_bf16 v[18:21], v[170:173], v[206:209], v[18:21]
	v_mfma_f32_16x16x32_bf16 v[10:13], v[178:181], v[206:209], v[10:13]
	v_mfma_f32_16x16x32_bf16 v[6:9], v[170:173], v[214:217], v[6:9]
	v_mfma_f32_16x16x32_bf16 v[2:5], v[178:181], v[214:217], v[2:5]
	v_mfma_f32_16x16x32_bf16 v[50:53], v[174:177], v[194:197], v[50:53]
	v_mfma_f32_16x16x32_bf16 v[42:45], v[182:185], v[194:197], v[42:45]
	v_mfma_f32_16x16x32_bf16 v[34:37], v[174:177], v[202:205], v[34:37]
	v_mfma_f32_16x16x32_bf16 v[26:29], v[182:185], v[202:205], v[26:29]
	v_mfma_f32_16x16x32_bf16 v[18:21], v[174:177], v[210:213], v[18:21]
	v_mfma_f32_16x16x32_bf16 v[10:13], v[182:185], v[210:213], v[10:13]
	v_mfma_f32_16x16x32_bf16 v[6:9], v[174:177], v[218:221], v[6:9]
	v_mfma_f32_16x16x32_bf16 v[2:5], v[182:185], v[218:221], v[2:5]
	s_barrier
	s_add_i32 s26, 0, 0x18000
	s_add_i32 s27, 0, 0x1c000
	v_add_u32_e32 v166, s26, v1
	v_add_u32_e32 v182, s27, v1
	ds_read_b128 v[154:157], v166
	ds_read_b128 v[158:161], v166 offset:1024
	ds_read_b128 v[162:165], v166 offset:2048
	ds_read_b128 v[166:169], v166 offset:3072
	ds_read_b128 v[170:173], v182
	ds_read_b128 v[174:177], v182 offset:1024
	ds_read_b128 v[178:181], v182 offset:2048
	ds_read_b128 v[182:185], v182 offset:3072
	s_add_u32 s24, s24, 0x80000
	s_addc_u32 s25, s25, 0
	s_mov_b32 m0, s74
	v_lshl_add_u64 v[228:229], s[24:25], 0, v[136:137]
	ds_read_b128 v[190:193], v151 offset:32768
	ds_read_b128 v[194:197], v151 offset:33792
	ds_read_b128 v[198:201], v151 offset:34816
	ds_read_b128 v[202:205], v151 offset:35840
	ds_read_b128 v[206:209], v151 offset:36864
	ds_read_b128 v[210:213], v151 offset:37888
	ds_read_b128 v[214:217], v151 offset:38912
	ds_read_b128 v[218:221], v151 offset:39936
	global_load_lds_dwordx4 v[228:229], off
	v_lshl_add_u64 v[228:229], s[24:25], 0, v[132:133]
	s_mov_b32 m0, s75
	s_nop 0
	global_load_lds_dwordx4 v[228:229], off
	s_waitcnt vmcnt(8)
	s_waitcnt lgkmcnt(0)
	s_barrier
	s_waitcnt lgkmcnt(0)
	v_mfma_f32_16x16x32_bf16 v[126:129], v[154:157], v[190:193], v[126:129]
	v_mfma_f32_16x16x32_bf16 v[122:125], v[162:165], v[190:193], v[122:125]
	v_mfma_f32_16x16x32_bf16 v[118:121], v[154:157], v[198:201], v[118:121]
	v_mfma_f32_16x16x32_bf16 v[110:113], v[162:165], v[198:201], v[110:113]
	v_mfma_f32_16x16x32_bf16 v[98:101], v[154:157], v[206:209], v[98:101]
	v_mfma_f32_16x16x32_bf16 v[90:93], v[162:165], v[206:209], v[90:93]
	v_mfma_f32_16x16x32_bf16 v[82:85], v[154:157], v[214:217], v[82:85]
	v_mfma_f32_16x16x32_bf16 v[74:77], v[162:165], v[214:217], v[74:77]
	v_mfma_f32_16x16x32_bf16 v[126:129], v[158:161], v[194:197], v[126:129]
	v_mfma_f32_16x16x32_bf16 v[122:125], v[166:169], v[194:197], v[122:125]
	v_mfma_f32_16x16x32_bf16 v[118:121], v[158:161], v[202:205], v[118:121]
	v_mfma_f32_16x16x32_bf16 v[110:113], v[166:169], v[202:205], v[110:113]
	v_mfma_f32_16x16x32_bf16 v[98:101], v[158:161], v[210:213], v[98:101]
	v_mfma_f32_16x16x32_bf16 v[90:93], v[166:169], v[210:213], v[90:93]
	v_mfma_f32_16x16x32_bf16 v[82:85], v[158:161], v[218:221], v[82:85]
	v_mfma_f32_16x16x32_bf16 v[74:77], v[166:169], v[218:221], v[74:77]
	v_mfma_f32_16x16x32_bf16 v[114:117], v[170:173], v[190:193], v[114:117]
	v_mfma_f32_16x16x32_bf16 v[106:109], v[178:181], v[190:193], v[106:109]
	v_mfma_f32_16x16x32_bf16 v[102:105], v[170:173], v[198:201], v[102:105]
	v_mfma_f32_16x16x32_bf16 v[94:97], v[178:181], v[198:201], v[94:97]
	v_mfma_f32_16x16x32_bf16 v[86:89], v[170:173], v[206:209], v[86:89]
	v_mfma_f32_16x16x32_bf16 v[78:81], v[178:181], v[206:209], v[78:81]
	v_mfma_f32_16x16x32_bf16 v[70:73], v[170:173], v[214:217], v[70:73]
	v_mfma_f32_16x16x32_bf16 v[66:69], v[178:181], v[214:217], v[66:69]
	v_mfma_f32_16x16x32_bf16 v[114:117], v[174:177], v[194:197], v[114:117]
	v_mfma_f32_16x16x32_bf16 v[106:109], v[182:185], v[194:197], v[106:109]
	v_mfma_f32_16x16x32_bf16 v[102:105], v[174:177], v[202:205], v[102:105]
	v_mfma_f32_16x16x32_bf16 v[94:97], v[182:185], v[202:205], v[94:97]
	v_mfma_f32_16x16x32_bf16 v[86:89], v[174:177], v[210:213], v[86:89]
	v_mfma_f32_16x16x32_bf16 v[78:81], v[182:185], v[210:213], v[78:81]
	v_mfma_f32_16x16x32_bf16 v[70:73], v[174:177], v[218:221], v[70:73]
	v_mfma_f32_16x16x32_bf16 v[66:69], v[182:185], v[218:221], v[66:69]
	s_barrier
	s_add_i32 s24, s26, s35
	v_lshl_add_u64 v[186:187], v[186:187], 0, s[6:7]
	s_mov_b32 m0, s24
	ds_read_b128 v[190:193], v151 offset:49152
	ds_read_b128 v[194:197], v151 offset:50176
	ds_read_b128 v[198:201], v151 offset:51200
	ds_read_b128 v[202:205], v151 offset:52224
	ds_read_b128 v[206:209], v151 offset:53248
	ds_read_b128 v[210:213], v151 offset:54272
	ds_read_b128 v[214:217], v151 offset:55296
	ds_read_b128 v[218:221], v151 offset:56320
	global_load_lds_dwordx4 v[186:187], off
	s_add_i32 m0, s24, 0x2000
	s_add_u32 s22, s22, 0x8080
	v_lshl_add_u64 v[186:187], v[222:223], 0, s[6:7]
	s_addc_u32 s23, s23, 0
	s_add_i32 s24, s27, s35
	global_load_lds_dwordx4 v[186:187], off
	v_lshl_add_u64 v[186:187], s[22:23], 0, v[134:135]
	s_mov_b32 m0, s24
	s_nop 0
	global_load_lds_dwordx4 v[186:187], off
	v_lshl_add_u64 v[186:187], s[22:23], 0, v[130:131]
	s_add_i32 m0, s24, 0x2000
	s_nop 0
	global_load_lds_dwordx4 v[186:187], off
	v_lshl_add_u64 v[186:187], v[224:225], 0, s[6:7]
	s_mov_b32 m0, s78
	s_nop 0
	global_load_lds_dwordx4 v[186:187], off
	v_lshl_add_u64 v[186:187], v[226:227], 0, s[6:7]
	s_mov_b32 m0, s79
	s_nop 0
	global_load_lds_dwordx4 v[186:187], off
	s_waitcnt vmcnt(8)
	s_waitcnt lgkmcnt(0)
	s_barrier
	s_waitcnt lgkmcnt(0)
	v_mfma_f32_16x16x32_bf16 v[62:65], v[154:157], v[190:193], v[62:65]
	v_mfma_f32_16x16x32_bf16 v[58:61], v[162:165], v[190:193], v[58:61]
	v_mfma_f32_16x16x32_bf16 v[54:57], v[154:157], v[198:201], v[54:57]
	v_mfma_f32_16x16x32_bf16 v[46:49], v[162:165], v[198:201], v[46:49]
	v_mfma_f32_16x16x32_bf16 v[38:41], v[154:157], v[206:209], v[38:41]
	v_mfma_f32_16x16x32_bf16 v[30:33], v[162:165], v[206:209], v[30:33]
	v_mfma_f32_16x16x32_bf16 v[22:25], v[154:157], v[214:217], v[22:25]
	v_mfma_f32_16x16x32_bf16 v[14:17], v[162:165], v[214:217], v[14:17]
	v_mfma_f32_16x16x32_bf16 v[62:65], v[158:161], v[194:197], v[62:65]
	v_mfma_f32_16x16x32_bf16 v[58:61], v[166:169], v[194:197], v[58:61]
	v_mfma_f32_16x16x32_bf16 v[54:57], v[158:161], v[202:205], v[54:57]
	v_mfma_f32_16x16x32_bf16 v[46:49], v[166:169], v[202:205], v[46:49]
	v_mfma_f32_16x16x32_bf16 v[38:41], v[158:161], v[210:213], v[38:41]
	v_mfma_f32_16x16x32_bf16 v[30:33], v[166:169], v[210:213], v[30:33]
	v_mfma_f32_16x16x32_bf16 v[22:25], v[158:161], v[218:221], v[22:25]
	v_mfma_f32_16x16x32_bf16 v[14:17], v[166:169], v[218:221], v[14:17]
	v_mfma_f32_16x16x32_bf16 v[50:53], v[170:173], v[190:193], v[50:53]
	v_mfma_f32_16x16x32_bf16 v[42:45], v[178:181], v[190:193], v[42:45]
	v_mfma_f32_16x16x32_bf16 v[34:37], v[170:173], v[198:201], v[34:37]
	v_mfma_f32_16x16x32_bf16 v[26:29], v[178:181], v[198:201], v[26:29]
	v_mfma_f32_16x16x32_bf16 v[18:21], v[170:173], v[206:209], v[18:21]
	v_mfma_f32_16x16x32_bf16 v[10:13], v[178:181], v[206:209], v[10:13]
	v_mfma_f32_16x16x32_bf16 v[6:9], v[170:173], v[214:217], v[6:9]
	v_mfma_f32_16x16x32_bf16 v[2:5], v[178:181], v[214:217], v[2:5]
	v_mfma_f32_16x16x32_bf16 v[50:53], v[174:177], v[194:197], v[50:53]
	v_mfma_f32_16x16x32_bf16 v[42:45], v[182:185], v[194:197], v[42:45]
	v_mfma_f32_16x16x32_bf16 v[34:37], v[174:177], v[202:205], v[34:37]
	v_mfma_f32_16x16x32_bf16 v[26:29], v[182:185], v[202:205], v[26:29]
	v_mfma_f32_16x16x32_bf16 v[18:21], v[174:177], v[210:213], v[18:21]
	v_mfma_f32_16x16x32_bf16 v[10:13], v[182:185], v[210:213], v[10:13]
	v_mfma_f32_16x16x32_bf16 v[6:9], v[174:177], v[218:221], v[6:9]
	v_mfma_f32_16x16x32_bf16 v[2:5], v[182:185], v[218:221], v[2:5]
	s_barrier
	s_add_i32 s86, s86, 2
	s_add_u32 s20, s20, 0x100
	s_addc_u32 s21, s21, 0
	s_add_u32 s97, s97, 0x100
	s_addc_u32 vcc_lo, vcc_lo, 0
	s_cmp_gt_u32 s86, 29
	s_cbranch_scc0 .LBB0_79
	s_and_b64 vcc, exec, s[8:9]
	s_cbranch_vccz .LBB0_82
	s_barrier

.LBB0_86:
	s_waitcnt vmcnt(0)
	s_waitcnt vmcnt(0)
	s_setprio 0
	s_barrier
	s_and_saveexec_b64 s[0:1], s[28:29]
	s_xor_b64 s[0:1], exec, s[0:1]
	s_cbranch_execz .LBB0_139
	s_add_i32 s2, 0, 0x24800
	v_mov_b32_e32 v1, s2
	s_waitcnt vmcnt(0) expcnt(0) lgkmcnt(0)
	ds_read_b32 v3, v1
	s_add_i32 s2, 0, 0x24804
	v_mov_b32_e32 v1, s2
	ds_read_b32 v1, v1
	s_waitcnt lgkmcnt(1)
	v_cmp_ne_u32_e32 vcc, 0, v3
	s_cbranch_vccnz .LBB0_102
	v_readlane_b32 s2, v253, 0
	s_mul_i32 s16, s69, s2
	s_add_u32 s2, s50, 0x1000
	s_addc_u32 s3, s51, 0
	s_add_u32 s4, s50, 0x1100
	s_addc_u32 s5, s51, 0
	s_add_u32 s6, s50, 0x1200
	s_addc_u32 s7, s51, 0
	s_add_u32 s8, s50, 0x1300
	s_mul_i32 s16, s16, s68
	s_addc_u32 s9, s51, 0
	s_mov_b32 s17, 1
	v_mov_b32_e32 v17, 0
	s_branch .LBB0_90

.LBB0_352:
	v_ashrrev_i32_e32 v1, 31, v8
	v_lshrrev_b32_e32 v1, 26, v1
	v_add_u32_e32 v1, v8, v1
	v_ashrrev_i32_e32 v9, 6, v1
	v_bfe_i32 v1, v8, 27, 1
	v_lshlrev_b32_e32 v0, 4, v8
	v_lshrrev_b32_e32 v1, 22, v1
	v_add_u32_e32 v1, v0, v1
	v_and_b32_e32 v1, 0xfffffc00, v1
	v_sub_u32_e32 v1, v0, v1
	v_lshrrev_b32_e32 v2, 4, v1
	v_bitop3_b32 v1, v2, v1, 32 bitop3:0x6c
	v_ashrrev_i32_e32 v3, 31, v1
	v_lshrrev_b32_e32 v3, 26, v3
	v_add_u32_e32 v3, v1, v3
	v_lshlrev_b32_e32 v2, 3, v9
	v_ashrrev_i32_e32 v11, 6, v3
	v_and_b32_e32 v3, 0xc0, v3
	v_and_b32_e32 v2, -16, v2
	v_sub_u32_e32 v1, v1, v3
	v_mov_b32_e32 v3, 1
	s_ashr_i32 s0, s3, 3
	v_add_u32_e32 v2, v11, v2
	v_lshlrev_b32_e32 v4, 5, v9
	v_ashrrev_i16_sdwa v1, v3, sext(v1) dst_sel:DWORD dst_unused:UNUSED_PAD src0_sel:DWORD src1_sel:BYTE_0
	v_and_b32_e32 v10, 32, v4
	v_bfe_i32 v12, v1, 0, 16
	v_lshlrev_b32_e32 v4, 1, v2
	v_lshlrev_b32_e32 v5, 2, v2
	v_lshrrev_b32_e32 v6, 2, v2
	v_and_b32_e32 v7, 3, v11
	s_movk_i32 s3, 0x3040
	s_add_i32 s0, s6, s0
	v_add_u32_e32 v1, v10, v12
	v_and_b32_e32 v4, 0x7ffc0, v4
	v_and_b32_e32 v6, 4, v6
	v_and_or_b32 v5, v5, 48, v7
	v_mul_lo_u32 v2, v2, s3
	s_ashr_i32 s1, s0, 31
	v_or3_b32 v4, v5, v4, v6
	v_add_lshl_u32 v128, v1, v2, 1
	v_lshlrev_b32_e32 v1, 1, v1
	v_add_u32_e32 v0, 0x2000, v0
	s_lshr_b32 s1, s1, 26
	v_lshl_add_u32 v130, v4, 13, v1
	v_ashrrev_i32_e32 v1, 31, v0
	s_add_i32 s1, s0, s1
	v_lshrrev_b32_e32 v1, 22, v1
	s_ashr_i32 s6, s1, 6
	s_andn2_b32 s1, s1, 63
	v_add_u32_e32 v1, v0, v1
	s_sub_i32 s1, s0, s1
	v_ashrrev_i32_e32 v13, 10, v1
	s_bfe_i32 s0, s1, 0x80000
	v_mul_i32_i24_e32 v1, 0x400, v13
	s_bfe_u32 s0, s0, 0x3000c
	v_sub_u32_e32 v0, v0, v1
	s_add_i32 s7, s1, s0
	v_lshrrev_b32_e32 v1, 4, v0
	s_bfe_i32 s0, s7, 0x80000
	s_and_b32 s7, s7, 0xf8
	v_bitop3_b32 v0, v1, v0, 32 bitop3:0x6c
	s_sub_i32 s1, s1, s7
	v_ashrrev_i32_e32 v2, 31, v0
	s_lshl_b32 s6, s6, 3
	s_sext_i32_i8 s1, s1
	v_lshrrev_b32_e32 v2, 26, v2
	s_sext_i32_i16 s0, s0
	s_add_i32 s96, s6, s1
	v_add_u32_e32 v2, v0, v2
	s_lshr_b32 s0, s0, 3
	s_mul_hi_i32 s1, s96, 0x608000
	s_ashr_i32 s4, s2, 6
	v_lshlrev_b32_e32 v1, 3, v13
	v_ashrrev_i32_e32 v14, 6, v2
	v_and_b32_e32 v2, 0xc0, v2
	s_bfe_i64 s[6:7], s[0:1], 0x100000
	v_and_b32_e32 v1, -16, v1
	v_sub_u32_e32 v0, v0, v2
	s_ashr_i32 s5, s2, 8
	s_lshl_b32 s35, s4, 10
	s_lshl_b64 s[6:7], s[6:7], 21
	v_add_u32_e32 v1, v14, v1
	v_lshlrev_b32_e32 v4, 5, v13
	v_ashrrev_i16_sdwa v0, v3, sext(v0) dst_sel:DWORD dst_unused:UNUSED_PAD src0_sel:DWORD src1_sel:BYTE_0
	s_add_u32 s22, s18, s6
	v_and_b32_e32 v15, 32, v4
	v_bfe_i32 v16, v0, 0, 16
	v_lshlrev_b32_e32 v2, 1, v1
	v_lshlrev_b32_e32 v3, 2, v1
	v_lshrrev_b32_e32 v4, 2, v1
	v_and_b32_e32 v5, 3, v14
	s_addc_u32 s23, s19, s7
	s_add_i32 s62, s35, 0
	v_add_u32_e32 v0, v15, v16
	v_and_b32_e32 v2, 0x7ffc0, v2
	v_and_b32_e32 v4, 4, v4
	v_and_or_b32 v3, v3, 48, v5
	v_mul_lo_u32 v1, v1, s3
	s_add_i32 m0, s62, 0x10000
	v_or3_b32 v2, v3, v2, v4
	v_add_lshl_u32 v132, v0, v1, 1
	v_lshlrev_b32_e32 v0, 1, v0
	global_load_lds_dwordx4 v130, s[22:23]
	s_add_i32 m0, s62, 0x12000
	v_lshl_add_u32 v134, v2, 13, v0
	s_add_u32 s6, s22, 0x10000
	global_load_lds_dwordx4 v134, s[22:23]
	s_addc_u32 s7, s23, 0
	s_add_i32 m0, s62, 0x14000
	s_mul_i32 s8, s96, 0x608000
	global_load_lds_dwordx4 v130, s[6:7]
	s_add_i32 m0, s62, 0x16000
	s_add_u32 s20, s76, s8
	s_addc_u32 s21, s77, s1
	s_add_i32 s63, s62, 0x2000
	global_load_lds_dwordx4 v134, s[6:7]
	s_mov_b32 m0, s62
	s_add_u32 s6, s20, 0x304000
	global_load_lds_dwordx4 v128, s[20:21]
	s_mov_b32 m0, s63
	s_addc_u32 s7, s21, 0
	s_add_i32 s64, s62, 0x4000
	global_load_lds_dwordx4 v132, s[20:21]
	s_mov_b32 m0, s64
	s_add_i32 s65, s62, 0x6000
	global_load_lds_dwordx4 v128, s[6:7]
	s_mov_b32 m0, s65
	v_mov_b32_e32 v137, 0
	global_load_lds_dwordx4 v132, s[6:7]
	v_mov_b32_e32 v131, v137
	v_mov_b32_e32 v135, v137
	v_mov_b32_e32 v129, v137
	v_mov_b32_e32 v133, v137
	s_cmp_eq_u32 s5, 1
	s_mov_b32 s1, 0
	v_lshl_add_u64 v[6:7], s[22:23], 0, v[130:131]
	v_lshl_add_u64 v[4:5], s[22:23], 0, v[134:135]
	v_lshl_add_u64 v[0:1], s[20:21], 0, v[128:129]
	s_cselect_b64 s[6:7], -1, 0
	s_cmp_lg_u32 s5, 1
	v_lshl_add_u64 v[2:3], s[20:21], 0, v[132:133]
	s_cbranch_scc1 .LBB0_354
	s_barrier
	s_setprio 1

.LBB0_366:
	ds_read_b128 v[154:157], v149
	ds_read_b128 v[158:161], v149 offset:1024
	ds_read_b128 v[162:165], v149 offset:2048
	ds_read_b128 v[166:169], v149 offset:3072
	ds_read_b128 v[170:173], v150
	ds_read_b128 v[174:177], v150 offset:1024
	ds_read_b128 v[178:181], v150 offset:2048
	ds_read_b128 v[182:185], v150 offset:3072
	s_add_u32 s4, s20, 0x100
	s_addc_u32 s5, s21, 0
	s_cmp_eq_u32 s74, 60
	s_cselect_b32 s25, s15, s5
	s_cselect_b32 s24, s14, s4
	s_cselect_b32 s23, s13, s86
	s_cselect_b32 s22, vcc_lo, vcc_hi
	v_lshl_add_u64 v[186:187], s[20:21], 0, v[138:139]
	s_add_i32 m0, s62, 0xc000
	ds_read_b128 v[190:193], v151
	ds_read_b128 v[194:197], v151 offset:1024
	ds_read_b128 v[198:201], v151 offset:2048
	ds_read_b128 v[202:205], v151 offset:3072
	ds_read_b128 v[206:209], v151 offset:4096
	ds_read_b128 v[210:213], v151 offset:5120
	ds_read_b128 v[214:217], v151 offset:6144
	ds_read_b128 v[218:221], v151 offset:7168
	global_load_lds_dwordx4 v[186:187], off
	v_lshl_add_u64 v[186:187], s[20:21], 0, v[140:141]
	s_add_i32 m0, s62, 0xe000
	s_nop 0
	global_load_lds_dwordx4 v[186:187], off
	s_waitcnt vmcnt(8)
	s_waitcnt lgkmcnt(0)
	s_barrier
	s_waitcnt lgkmcnt(0)
	v_mfma_f32_16x16x32_bf16 v[124:127], v[154:157], v[190:193], v[124:127]
	v_mfma_f32_16x16x32_bf16 v[120:123], v[162:165], v[190:193], v[120:123]
	v_mfma_f32_16x16x32_bf16 v[116:119], v[154:157], v[198:201], v[116:119]
	v_mfma_f32_16x16x32_bf16 v[108:111], v[162:165], v[198:201], v[108:111]
	v_mfma_f32_16x16x32_bf16 v[96:99], v[154:157], v[206:209], v[96:99]
	v_mfma_f32_16x16x32_bf16 v[88:91], v[162:165], v[206:209], v[88:91]
	v_mfma_f32_16x16x32_bf16 v[84:87], v[154:157], v[214:217], v[84:87]
	v_mfma_f32_16x16x32_bf16 v[76:79], v[162:165], v[214:217], v[76:79]
	v_mfma_f32_16x16x32_bf16 v[124:127], v[158:161], v[194:197], v[124:127]
	v_mfma_f32_16x16x32_bf16 v[120:123], v[166:169], v[194:197], v[120:123]
	v_mfma_f32_16x16x32_bf16 v[116:119], v[158:161], v[202:205], v[116:119]
	v_mfma_f32_16x16x32_bf16 v[108:111], v[166:169], v[202:205], v[108:111]
	v_mfma_f32_16x16x32_bf16 v[96:99], v[158:161], v[210:213], v[96:99]
	v_mfma_f32_16x16x32_bf16 v[88:91], v[166:169], v[210:213], v[88:91]
	v_mfma_f32_16x16x32_bf16 v[84:87], v[158:161], v[218:221], v[84:87]
	v_mfma_f32_16x16x32_bf16 v[76:79], v[166:169], v[218:221], v[76:79]
	v_mfma_f32_16x16x32_bf16 v[112:115], v[170:173], v[190:193], v[112:115]
	v_mfma_f32_16x16x32_bf16 v[104:107], v[178:181], v[190:193], v[104:107]
	v_mfma_f32_16x16x32_bf16 v[100:103], v[170:173], v[198:201], v[100:103]
	v_mfma_f32_16x16x32_bf16 v[92:95], v[178:181], v[198:201], v[92:95]
	v_mfma_f32_16x16x32_bf16 v[80:83], v[170:173], v[206:209], v[80:83]
	v_mfma_f32_16x16x32_bf16 v[72:75], v[178:181], v[206:209], v[72:75]
	v_mfma_f32_16x16x32_bf16 v[68:71], v[170:173], v[214:217], v[68:71]
	v_mfma_f32_16x16x32_bf16 v[64:67], v[178:181], v[214:217], v[64:67]
	v_mfma_f32_16x16x32_bf16 v[112:115], v[174:177], v[194:197], v[112:115]
	v_mfma_f32_16x16x32_bf16 v[104:107], v[182:185], v[194:197], v[104:107]
	v_mfma_f32_16x16x32_bf16 v[100:103], v[174:177], v[202:205], v[100:103]
	v_mfma_f32_16x16x32_bf16 v[92:95], v[182:185], v[202:205], v[92:95]
	v_mfma_f32_16x16x32_bf16 v[80:83], v[174:177], v[210:213], v[80:83]
	v_mfma_f32_16x16x32_bf16 v[72:75], v[182:185], v[210:213], v[72:75]
	v_mfma_f32_16x16x32_bf16 v[68:71], v[174:177], v[218:221], v[68:71]
	v_mfma_f32_16x16x32_bf16 v[64:67], v[182:185], v[218:221], v[64:67]
	s_barrier
	s_add_i32 s20, s78, s35
	v_lshl_add_u64 v[186:187], s[22:23], 0, v[130:131]
	s_mov_b32 m0, s20
	ds_read_b128 v[190:193], v151 offset:16384
	ds_read_b128 v[194:197], v151 offset:17408
	ds_read_b128 v[198:201], v151 offset:18432
	ds_read_b128 v[202:205], v151 offset:19456
	ds_read_b128 v[206:209], v151 offset:20480
	ds_read_b128 v[210:213], v151 offset:21504
	ds_read_b128 v[214:217], v151 offset:22528
	ds_read_b128 v[218:221], v151 offset:23552
	global_load_lds_dwordx4 v[186:187], off
	s_add_i32 m0, s20, 0x2000
	s_add_u32 s20, s22, 0x10000
	v_lshl_add_u64 v[222:223], s[22:23], 0, v[134:135]
	s_addc_u32 s21, s23, 0
	s_add_i32 s26, s79, s35
	global_load_lds_dwordx4 v[222:223], off
	v_lshl_add_u64 v[224:225], s[20:21], 0, v[130:131]
	s_mov_b32 m0, s26
	v_lshl_add_u64 v[226:227], s[24:25], 0, v[132:133]
	global_load_lds_dwordx4 v[224:225], off
	v_lshl_add_u64 v[224:225], s[20:21], 0, v[134:135]
	s_add_i32 m0, s26, 0x2000
	s_nop 0
	global_load_lds_dwordx4 v[224:225], off
	v_lshl_add_u64 v[224:225], s[24:25], 0, v[128:129]
	s_mov_b32 m0, s62
	s_nop 0
	global_load_lds_dwordx4 v[224:225], off
	s_mov_b32 m0, s63
	s_nop 0
	global_load_lds_dwordx4 v[226:227], off
	s_waitcnt vmcnt(8)
	s_waitcnt lgkmcnt(0)
	s_barrier
	s_waitcnt lgkmcnt(0)
	v_mfma_f32_16x16x32_bf16 v[60:63], v[154:157], v[190:193], v[60:63]
	v_mfma_f32_16x16x32_bf16 v[56:59], v[162:165], v[190:193], v[56:59]
	v_mfma_f32_16x16x32_bf16 v[52:55], v[154:157], v[198:201], v[52:55]
	v_mfma_f32_16x16x32_bf16 v[44:47], v[162:165], v[198:201], v[44:47]
	v_mfma_f32_16x16x32_bf16 v[36:39], v[154:157], v[206:209], v[36:39]
	v_mfma_f32_16x16x32_bf16 v[28:31], v[162:165], v[206:209], v[28:31]
	v_mfma_f32_16x16x32_bf16 v[20:23], v[154:157], v[214:217], v[20:23]
	v_mfma_f32_16x16x32_bf16 v[12:15], v[162:165], v[214:217], v[12:15]
	v_mfma_f32_16x16x32_bf16 v[60:63], v[158:161], v[194:197], v[60:63]
	v_mfma_f32_16x16x32_bf16 v[56:59], v[166:169], v[194:197], v[56:59]
	v_mfma_f32_16x16x32_bf16 v[52:55], v[158:161], v[202:205], v[52:55]
	v_mfma_f32_16x16x32_bf16 v[44:47], v[166:169], v[202:205], v[44:47]
	v_mfma_f32_16x16x32_bf16 v[36:39], v[158:161], v[210:213], v[36:39]
	v_mfma_f32_16x16x32_bf16 v[28:31], v[166:169], v[210:213], v[28:31]
	v_mfma_f32_16x16x32_bf16 v[20:23], v[158:161], v[218:221], v[20:23]
	v_mfma_f32_16x16x32_bf16 v[12:15], v[166:169], v[218:221], v[12:15]
	v_mfma_f32_16x16x32_bf16 v[48:51], v[170:173], v[190:193], v[48:51]
	v_mfma_f32_16x16x32_bf16 v[40:43], v[178:181], v[190:193], v[40:43]
	v_mfma_f32_16x16x32_bf16 v[32:35], v[170:173], v[198:201], v[32:35]
	v_mfma_f32_16x16x32_bf16 v[24:27], v[178:181], v[198:201], v[24:27]
	v_mfma_f32_16x16x32_bf16 v[16:19], v[170:173], v[206:209], v[16:19]
	v_mfma_f32_16x16x32_bf16 v[8:11], v[178:181], v[206:209], v[8:11]
	v_mfma_f32_16x16x32_bf16 v[4:7], v[170:173], v[214:217], v[4:7]
	v_mfma_f32_16x16x32_bf16 v[0:3], v[178:181], v[214:217], v[0:3]
	v_mfma_f32_16x16x32_bf16 v[48:51], v[174:177], v[194:197], v[48:51]
	v_mfma_f32_16x16x32_bf16 v[40:43], v[182:185], v[194:197], v[40:43]
	v_mfma_f32_16x16x32_bf16 v[32:35], v[174:177], v[202:205], v[32:35]
	v_mfma_f32_16x16x32_bf16 v[24:27], v[182:185], v[202:205], v[24:27]
	v_mfma_f32_16x16x32_bf16 v[16:19], v[174:177], v[210:213], v[16:19]
	v_mfma_f32_16x16x32_bf16 v[8:11], v[182:185], v[210:213], v[8:11]
	v_mfma_f32_16x16x32_bf16 v[4:7], v[174:177], v[218:221], v[4:7]
	v_mfma_f32_16x16x32_bf16 v[0:3], v[182:185], v[218:221], v[0:3]
	s_barrier
	s_add_i32 s26, 0, 0x18000
	s_add_i32 s27, 0, 0x1c000
	v_add_u32_e32 v166, s26, v147
	v_add_u32_e32 v182, s27, v147
	ds_read_b128 v[154:157], v166
	ds_read_b128 v[158:161], v166 offset:1024
	ds_read_b128 v[162:165], v166 offset:2048
	ds_read_b128 v[166:169], v166 offset:3072
	ds_read_b128 v[170:173], v182
	ds_read_b128 v[174:177], v182 offset:1024
	ds_read_b128 v[178:181], v182 offset:2048
	ds_read_b128 v[182:185], v182 offset:3072
	s_add_u32 s20, s24, 0x304000
	s_addc_u32 s21, s25, 0
	s_mov_b32 m0, s64
	v_lshl_add_u64 v[228:229], s[20:21], 0, v[128:129]
	ds_read_b128 v[190:193], v151 offset:32768
	ds_read_b128 v[194:197], v151 offset:33792
	ds_read_b128 v[198:201], v151 offset:34816
	ds_read_b128 v[202:205], v151 offset:35840
	ds_read_b128 v[206:209], v151 offset:36864
	ds_read_b128 v[210:213], v151 offset:37888
	ds_read_b128 v[214:217], v151 offset:38912
	ds_read_b128 v[218:221], v151 offset:39936
	global_load_lds_dwordx4 v[228:229], off
	v_lshl_add_u64 v[228:229], s[20:21], 0, v[132:133]
	s_mov_b32 m0, s65
	s_nop 0
	global_load_lds_dwordx4 v[228:229], off
	s_waitcnt vmcnt(8)
	s_waitcnt lgkmcnt(0)
	s_barrier
	s_waitcnt lgkmcnt(0)
	v_mfma_f32_16x16x32_bf16 v[124:127], v[154:157], v[190:193], v[124:127]
	v_mfma_f32_16x16x32_bf16 v[120:123], v[162:165], v[190:193], v[120:123]
	v_mfma_f32_16x16x32_bf16 v[116:119], v[154:157], v[198:201], v[116:119]
	v_mfma_f32_16x16x32_bf16 v[108:111], v[162:165], v[198:201], v[108:111]
	v_mfma_f32_16x16x32_bf16 v[96:99], v[154:157], v[206:209], v[96:99]
	v_mfma_f32_16x16x32_bf16 v[88:91], v[162:165], v[206:209], v[88:91]
	v_mfma_f32_16x16x32_bf16 v[84:87], v[154:157], v[214:217], v[84:87]
	v_mfma_f32_16x16x32_bf16 v[76:79], v[162:165], v[214:217], v[76:79]
	v_mfma_f32_16x16x32_bf16 v[124:127], v[158:161], v[194:197], v[124:127]
	v_mfma_f32_16x16x32_bf16 v[120:123], v[166:169], v[194:197], v[120:123]
	v_mfma_f32_16x16x32_bf16 v[116:119], v[158:161], v[202:205], v[116:119]
	v_mfma_f32_16x16x32_bf16 v[108:111], v[166:169], v[202:205], v[108:111]
	v_mfma_f32_16x16x32_bf16 v[96:99], v[158:161], v[210:213], v[96:99]
	v_mfma_f32_16x16x32_bf16 v[88:91], v[166:169], v[210:213], v[88:91]
	v_mfma_f32_16x16x32_bf16 v[84:87], v[158:161], v[218:221], v[84:87]
	v_mfma_f32_16x16x32_bf16 v[76:79], v[166:169], v[218:221], v[76:79]
	v_mfma_f32_16x16x32_bf16 v[112:115], v[170:173], v[190:193], v[112:115]
	v_mfma_f32_16x16x32_bf16 v[104:107], v[178:181], v[190:193], v[104:107]
	v_mfma_f32_16x16x32_bf16 v[100:103], v[170:173], v[198:201], v[100:103]
	v_mfma_f32_16x16x32_bf16 v[92:95], v[178:181], v[198:201], v[92:95]
	v_mfma_f32_16x16x32_bf16 v[80:83], v[170:173], v[206:209], v[80:83]
	v_mfma_f32_16x16x32_bf16 v[72:75], v[178:181], v[206:209], v[72:75]
	v_mfma_f32_16x16x32_bf16 v[68:71], v[170:173], v[214:217], v[68:71]
	v_mfma_f32_16x16x32_bf16 v[64:67], v[178:181], v[214:217], v[64:67]
	v_mfma_f32_16x16x32_bf16 v[112:115], v[174:177], v[194:197], v[112:115]
	v_mfma_f32_16x16x32_bf16 v[104:107], v[182:185], v[194:197], v[104:107]
	v_mfma_f32_16x16x32_bf16 v[100:103], v[174:177], v[202:205], v[100:103]
	v_mfma_f32_16x16x32_bf16 v[92:95], v[182:185], v[202:205], v[92:95]
	v_mfma_f32_16x16x32_bf16 v[80:83], v[174:177], v[210:213], v[80:83]
	v_mfma_f32_16x16x32_bf16 v[72:75], v[182:185], v[210:213], v[72:75]
	v_mfma_f32_16x16x32_bf16 v[68:71], v[174:177], v[218:221], v[68:71]
	v_mfma_f32_16x16x32_bf16 v[64:67], v[182:185], v[218:221], v[64:67]
	s_barrier
	s_add_i32 s20, s26, s35
	v_lshl_add_u64 v[186:187], v[186:187], 0, s[8:9]
	s_mov_b32 m0, s20
	ds_read_b128 v[190:193], v151 offset:49152
	ds_read_b128 v[194:197], v151 offset:50176
	ds_read_b128 v[198:201], v151 offset:51200
	ds_read_b128 v[202:205], v151 offset:52224
	ds_read_b128 v[206:209], v151 offset:53248
	ds_read_b128 v[210:213], v151 offset:54272
	ds_read_b128 v[214:217], v151 offset:55296
	ds_read_b128 v[218:221], v151 offset:56320
	global_load_lds_dwordx4 v[186:187], off
	s_add_i32 m0, s20, 0x2000
	s_add_u32 s20, s22, 0x10080
	v_lshl_add_u64 v[186:187], v[222:223], 0, s[8:9]
	s_addc_u32 s21, s23, 0
	s_add_i32 s22, s27, s35
	global_load_lds_dwordx4 v[186:187], off
	v_lshl_add_u64 v[186:187], s[20:21], 0, v[130:131]
	s_mov_b32 m0, s22
	s_nop 0
	global_load_lds_dwordx4 v[186:187], off
	v_lshl_add_u64 v[186:187], s[20:21], 0, v[134:135]
	s_add_i32 m0, s22, 0x2000
	s_nop 0
	global_load_lds_dwordx4 v[186:187], off
	v_lshl_add_u64 v[186:187], v[224:225], 0, s[8:9]
	s_mov_b32 m0, s66
	s_nop 0
	global_load_lds_dwordx4 v[186:187], off
	v_lshl_add_u64 v[186:187], v[226:227], 0, s[8:9]
	s_mov_b32 m0, s67
	s_nop 0
	global_load_lds_dwordx4 v[186:187], off
	s_waitcnt vmcnt(8)
	s_waitcnt lgkmcnt(0)
	s_barrier
	s_waitcnt lgkmcnt(0)
	v_mfma_f32_16x16x32_bf16 v[60:63], v[154:157], v[190:193], v[60:63]
	v_mfma_f32_16x16x32_bf16 v[56:59], v[162:165], v[190:193], v[56:59]
	v_mfma_f32_16x16x32_bf16 v[52:55], v[154:157], v[198:201], v[52:55]
	v_mfma_f32_16x16x32_bf16 v[44:47], v[162:165], v[198:201], v[44:47]
	v_mfma_f32_16x16x32_bf16 v[36:39], v[154:157], v[206:209], v[36:39]
	v_mfma_f32_16x16x32_bf16 v[28:31], v[162:165], v[206:209], v[28:31]
	v_mfma_f32_16x16x32_bf16 v[20:23], v[154:157], v[214:217], v[20:23]
	v_mfma_f32_16x16x32_bf16 v[12:15], v[162:165], v[214:217], v[12:15]
	v_mfma_f32_16x16x32_bf16 v[60:63], v[158:161], v[194:197], v[60:63]
	v_mfma_f32_16x16x32_bf16 v[56:59], v[166:169], v[194:197], v[56:59]
	v_mfma_f32_16x16x32_bf16 v[52:55], v[158:161], v[202:205], v[52:55]
	v_mfma_f32_16x16x32_bf16 v[44:47], v[166:169], v[202:205], v[44:47]
	v_mfma_f32_16x16x32_bf16 v[36:39], v[158:161], v[210:213], v[36:39]
	v_mfma_f32_16x16x32_bf16 v[28:31], v[166:169], v[210:213], v[28:31]
	v_mfma_f32_16x16x32_bf16 v[20:23], v[158:161], v[218:221], v[20:23]
	v_mfma_f32_16x16x32_bf16 v[12:15], v[166:169], v[218:221], v[12:15]
	v_mfma_f32_16x16x32_bf16 v[48:51], v[170:173], v[190:193], v[48:51]
	v_mfma_f32_16x16x32_bf16 v[40:43], v[178:181], v[190:193], v[40:43]
	v_mfma_f32_16x16x32_bf16 v[32:35], v[170:173], v[198:201], v[32:35]
	v_mfma_f32_16x16x32_bf16 v[24:27], v[178:181], v[198:201], v[24:27]
	v_mfma_f32_16x16x32_bf16 v[16:19], v[170:173], v[206:209], v[16:19]
	v_mfma_f32_16x16x32_bf16 v[8:11], v[178:181], v[206:209], v[8:11]
	v_mfma_f32_16x16x32_bf16 v[4:7], v[170:173], v[214:217], v[4:7]
	v_mfma_f32_16x16x32_bf16 v[0:3], v[178:181], v[214:217], v[0:3]
	v_mfma_f32_16x16x32_bf16 v[48:51], v[174:177], v[194:197], v[48:51]
	v_mfma_f32_16x16x32_bf16 v[40:43], v[182:185], v[194:197], v[40:43]
	v_mfma_f32_16x16x32_bf16 v[32:35], v[174:177], v[202:205], v[32:35]
	v_mfma_f32_16x16x32_bf16 v[24:27], v[182:185], v[202:205], v[24:27]
	v_mfma_f32_16x16x32_bf16 v[16:19], v[174:177], v[210:213], v[16:19]
	v_mfma_f32_16x16x32_bf16 v[8:11], v[182:185], v[210:213], v[8:11]
	v_mfma_f32_16x16x32_bf16 v[4:7], v[174:177], v[218:221], v[4:7]
	v_mfma_f32_16x16x32_bf16 v[0:3], v[182:185], v[218:221], v[0:3]
	s_barrier
	s_add_i32 s74, s74, 2
	s_add_u32 vcc_hi, vcc_hi, 0x100
	s_addc_u32 s86, s86, 0
	s_cmp_gt_u32 s74, 61
	s_mov_b64 s[20:21], s[4:5]
	s_cbranch_scc0 .LBB0_366
	s_and_b64 vcc, exec, s[10:11]
	s_cbranch_vccz .LBB0_369
	s_barrier

.LBB0_393:
	v_ashrrev_i32_e32 v1, 31, v8
	v_lshrrev_b32_e32 v1, 26, v1
	v_add_u32_e32 v1, v8, v1
	v_ashrrev_i32_e32 v9, 6, v1
	v_bfe_i32 v1, v8, 27, 1
	v_lshlrev_b32_e32 v0, 4, v8
	v_lshrrev_b32_e32 v1, 22, v1
	v_add_u32_e32 v1, v0, v1
	v_and_b32_e32 v1, 0xfffffc00, v1
	v_sub_u32_e32 v1, v0, v1
	v_lshrrev_b32_e32 v2, 4, v1
	v_bitop3_b32 v1, v2, v1, 32 bitop3:0x6c
	v_ashrrev_i32_e32 v3, 31, v1
	v_lshrrev_b32_e32 v3, 26, v3
	v_add_u32_e32 v3, v1, v3
	v_lshlrev_b32_e32 v2, 3, v9
	v_ashrrev_i32_e32 v11, 6, v3
	v_and_b32_e32 v3, 0xc0, v3
	v_and_b32_e32 v2, -16, v2
	v_sub_u32_e32 v1, v1, v3
	v_mov_b32_e32 v3, 1
	s_ashr_i32 s0, s3, 3
	v_add_u32_e32 v2, v11, v2
	v_lshlrev_b32_e32 v4, 5, v9
	v_ashrrev_i16_sdwa v1, v3, sext(v1) dst_sel:DWORD dst_unused:UNUSED_PAD src0_sel:DWORD src1_sel:BYTE_0
	v_and_b32_e32 v10, 32, v4
	v_bfe_i32 v12, v1, 0, 16
	v_lshlrev_b32_e32 v4, 1, v2
	v_lshlrev_b32_e32 v5, 2, v2
	v_lshrrev_b32_e32 v6, 2, v2
	v_and_b32_e32 v7, 3, v11
	s_movk_i32 s3, 0x3040
	s_add_i32 s0, s6, s0
	v_add_u32_e32 v1, v10, v12
	v_and_b32_e32 v4, 0x7ffc0, v4
	v_and_b32_e32 v6, 4, v6
	v_and_or_b32 v5, v5, 48, v7
	v_mul_lo_u32 v2, v2, s3
	s_ashr_i32 s1, s0, 31
	v_or3_b32 v4, v5, v4, v6
	v_add_lshl_u32 v128, v1, v2, 1
	v_lshlrev_b32_e32 v1, 1, v1
	v_add_u32_e32 v0, 0x2000, v0
	s_lshr_b32 s1, s1, 26
	v_lshl_add_u32 v130, v4, 13, v1
	v_ashrrev_i32_e32 v1, 31, v0
	s_add_i32 s1, s0, s1
	v_lshrrev_b32_e32 v1, 22, v1
	s_ashr_i32 s6, s1, 6
	s_andn2_b32 s1, s1, 63
	v_add_u32_e32 v1, v0, v1
	s_sub_i32 s1, s0, s1
	v_ashrrev_i32_e32 v13, 10, v1
	s_bfe_i32 s0, s1, 0x80000
	v_mul_i32_i24_e32 v1, 0x400, v13
	s_bfe_u32 s0, s0, 0x3000c
	v_sub_u32_e32 v0, v0, v1
	s_add_i32 s7, s1, s0
	v_lshrrev_b32_e32 v1, 4, v0
	s_bfe_i32 s0, s7, 0x80000
	s_and_b32 s7, s7, 0xf8
	v_bitop3_b32 v0, v1, v0, 32 bitop3:0x6c
	s_sub_i32 s1, s1, s7
	v_ashrrev_i32_e32 v2, 31, v0
	s_lshl_b32 s6, s6, 3
	s_sext_i32_i8 s1, s1
	v_lshrrev_b32_e32 v2, 26, v2
	s_sext_i32_i16 s0, s0
	s_add_i32 s13, s6, s1
	v_add_u32_e32 v2, v0, v2
	s_lshr_b32 s0, s0, 3
	s_mul_hi_i32 s1, s13, 0x608000
	s_ashr_i32 s4, s2, 6
	v_lshlrev_b32_e32 v1, 3, v13
	v_ashrrev_i32_e32 v14, 6, v2
	v_and_b32_e32 v2, 0xc0, v2
	s_bfe_i64 s[6:7], s[0:1], 0x100000
	v_and_b32_e32 v1, -16, v1
	v_sub_u32_e32 v0, v0, v2
	s_ashr_i32 s5, s2, 8
	s_lshl_b32 s35, s4, 10
	s_lshl_b64 s[6:7], s[6:7], 21
	v_add_u32_e32 v1, v14, v1
	v_lshlrev_b32_e32 v4, 5, v13
	v_ashrrev_i16_sdwa v0, v3, sext(v0) dst_sel:DWORD dst_unused:UNUSED_PAD src0_sel:DWORD src1_sel:BYTE_0
	s_add_u32 s24, s18, s6
	v_and_b32_e32 v15, 32, v4
	v_bfe_i32 v16, v0, 0, 16
	v_lshlrev_b32_e32 v2, 1, v1
	v_lshlrev_b32_e32 v3, 2, v1
	v_lshrrev_b32_e32 v4, 2, v1
	v_and_b32_e32 v5, 3, v14
	s_addc_u32 s25, s19, s7
	s_add_i32 s62, s35, 0
	v_add_u32_e32 v0, v15, v16
	v_and_b32_e32 v2, 0x7ffc0, v2
	v_and_b32_e32 v4, 4, v4
	v_and_or_b32 v3, v3, 48, v5
	v_mul_lo_u32 v1, v1, s3
	s_add_i32 m0, s62, 0x10000
	v_or3_b32 v2, v3, v2, v4
	v_add_lshl_u32 v132, v0, v1, 1
	v_lshlrev_b32_e32 v0, 1, v0
	global_load_lds_dwordx4 v130, s[24:25]
	s_add_i32 m0, s62, 0x12000
	v_lshl_add_u32 v134, v2, 13, v0
	s_add_u32 s6, s24, 0x10000
	global_load_lds_dwordx4 v134, s[24:25]
	s_addc_u32 s7, s25, 0
	s_add_i32 m0, s62, 0x14000
	s_mul_i32 s8, s13, 0x608000
	global_load_lds_dwordx4 v130, s[6:7]
	s_add_i32 m0, s62, 0x16000
	s_add_u32 s22, s76, s8
	s_addc_u32 s23, s77, s1
	s_add_i32 s63, s62, 0x2000
	global_load_lds_dwordx4 v134, s[6:7]
	s_mov_b32 m0, s62
	s_add_u32 s6, s22, 0x304000
	global_load_lds_dwordx4 v128, s[22:23]
	s_mov_b32 m0, s63
	s_addc_u32 s7, s23, 0
	s_add_i32 s64, s62, 0x4000
	global_load_lds_dwordx4 v132, s[22:23]
	s_mov_b32 m0, s64
	s_add_i32 s65, s62, 0x6000
	global_load_lds_dwordx4 v128, s[6:7]
	s_mov_b32 m0, s65
	v_mov_b32_e32 v137, 0
	global_load_lds_dwordx4 v132, s[6:7]
	v_mov_b32_e32 v131, v137
	v_mov_b32_e32 v135, v137
	v_mov_b32_e32 v129, v137
	v_mov_b32_e32 v133, v137
	s_cmp_eq_u32 s5, 1
	s_mov_b32 s1, 0
	v_lshl_add_u64 v[6:7], s[24:25], 0, v[130:131]
	v_lshl_add_u64 v[4:5], s[24:25], 0, v[134:135]
	v_lshl_add_u64 v[0:1], s[22:23], 0, v[128:129]
	s_cselect_b64 s[6:7], -1, 0
	s_cmp_lg_u32 s5, 1
	v_lshl_add_u64 v[2:3], s[22:23], 0, v[132:133]
	s_cbranch_scc1 .LBB0_395
	s_barrier
	s_setprio 1

.LBB0_408:
	ds_read_b128 v[154:157], v149
	ds_read_b128 v[158:161], v149 offset:1024
	ds_read_b128 v[162:165], v149 offset:2048
	ds_read_b128 v[166:169], v149 offset:3072
	ds_read_b128 v[170:173], v150
	ds_read_b128 v[174:177], v150 offset:1024
	ds_read_b128 v[178:181], v150 offset:2048
	ds_read_b128 v[182:185], v150 offset:3072
	s_mov_b32 s96, s95
	s_mov_b64 s[26:27], s[22:23]
	s_add_i32 s95, s95, 2
	s_add_u32 s22, s26, 0x100
	s_addc_u32 s23, s27, 0
	s_cmp_eq_u32 s94, 0
	s_cselect_b32 s25, s17, s23
	s_cselect_b32 s24, s16, s22
	s_cselect_b32 s5, s15, s86
	s_cselect_b32 s4, s74, s75
	v_lshl_add_u64 v[186:187], s[26:27], 0, v[138:139]
	s_add_i32 m0, s62, 0xc000
	ds_read_b128 v[190:193], v151
	ds_read_b128 v[194:197], v151 offset:1024
	ds_read_b128 v[198:201], v151 offset:2048
	ds_read_b128 v[202:205], v151 offset:3072
	ds_read_b128 v[206:209], v151 offset:4096
	ds_read_b128 v[210:213], v151 offset:5120
	ds_read_b128 v[214:217], v151 offset:6144
	ds_read_b128 v[218:221], v151 offset:7168
	global_load_lds_dwordx4 v[186:187], off
	v_lshl_add_u64 v[186:187], s[26:27], 0, v[140:141]
	s_add_i32 m0, s62, 0xe000
	s_nop 0
	global_load_lds_dwordx4 v[186:187], off
	s_waitcnt vmcnt(8)
	s_waitcnt lgkmcnt(0)
	s_barrier
	s_waitcnt lgkmcnt(0)
	v_mfma_f32_16x16x32_bf16 v[124:127], v[154:157], v[190:193], v[124:127]
	v_mfma_f32_16x16x32_bf16 v[120:123], v[162:165], v[190:193], v[120:123]
	v_mfma_f32_16x16x32_bf16 v[108:111], v[154:157], v[198:201], v[108:111]
	v_mfma_f32_16x16x32_bf16 v[104:107], v[162:165], v[198:201], v[104:107]
	v_mfma_f32_16x16x32_bf16 v[92:95], v[154:157], v[206:209], v[92:95]
	v_mfma_f32_16x16x32_bf16 v[88:91], v[162:165], v[206:209], v[88:91]
	v_mfma_f32_16x16x32_bf16 v[76:79], v[154:157], v[214:217], v[76:79]
	v_mfma_f32_16x16x32_bf16 v[72:75], v[162:165], v[214:217], v[72:75]
	v_mfma_f32_16x16x32_bf16 v[124:127], v[158:161], v[194:197], v[124:127]
	v_mfma_f32_16x16x32_bf16 v[120:123], v[166:169], v[194:197], v[120:123]
	v_mfma_f32_16x16x32_bf16 v[108:111], v[158:161], v[202:205], v[108:111]
	v_mfma_f32_16x16x32_bf16 v[104:107], v[166:169], v[202:205], v[104:107]
	v_mfma_f32_16x16x32_bf16 v[92:95], v[158:161], v[210:213], v[92:95]
	v_mfma_f32_16x16x32_bf16 v[88:91], v[166:169], v[210:213], v[88:91]
	v_mfma_f32_16x16x32_bf16 v[76:79], v[158:161], v[218:221], v[76:79]
	v_mfma_f32_16x16x32_bf16 v[72:75], v[166:169], v[218:221], v[72:75]
	v_mfma_f32_16x16x32_bf16 v[116:119], v[170:173], v[190:193], v[116:119]
	v_mfma_f32_16x16x32_bf16 v[112:115], v[178:181], v[190:193], v[112:115]
	v_mfma_f32_16x16x32_bf16 v[100:103], v[170:173], v[198:201], v[100:103]
	v_mfma_f32_16x16x32_bf16 v[96:99], v[178:181], v[198:201], v[96:99]
	v_mfma_f32_16x16x32_bf16 v[84:87], v[170:173], v[206:209], v[84:87]
	v_mfma_f32_16x16x32_bf16 v[80:83], v[178:181], v[206:209], v[80:83]
	v_mfma_f32_16x16x32_bf16 v[68:71], v[170:173], v[214:217], v[68:71]
	v_mfma_f32_16x16x32_bf16 v[64:67], v[178:181], v[214:217], v[64:67]
	v_mfma_f32_16x16x32_bf16 v[116:119], v[174:177], v[194:197], v[116:119]
	v_mfma_f32_16x16x32_bf16 v[112:115], v[182:185], v[194:197], v[112:115]
	v_mfma_f32_16x16x32_bf16 v[100:103], v[174:177], v[202:205], v[100:103]
	v_mfma_f32_16x16x32_bf16 v[96:99], v[182:185], v[202:205], v[96:99]
	v_mfma_f32_16x16x32_bf16 v[84:87], v[174:177], v[210:213], v[84:87]
	v_mfma_f32_16x16x32_bf16 v[80:83], v[182:185], v[210:213], v[80:83]
	v_mfma_f32_16x16x32_bf16 v[68:71], v[174:177], v[218:221], v[68:71]
	v_mfma_f32_16x16x32_bf16 v[64:67], v[182:185], v[218:221], v[64:67]
	s_barrier
	s_add_i32 s26, s78, s35
	v_lshl_add_u64 v[186:187], s[4:5], 0, v[130:131]
	s_mov_b32 m0, s26
	ds_read_b128 v[190:193], v151 offset:16384
	ds_read_b128 v[194:197], v151 offset:17408
	ds_read_b128 v[198:201], v151 offset:18432
	ds_read_b128 v[202:205], v151 offset:19456
	ds_read_b128 v[206:209], v151 offset:20480
	ds_read_b128 v[210:213], v151 offset:21504
	ds_read_b128 v[214:217], v151 offset:22528
	ds_read_b128 v[218:221], v151 offset:23552
	global_load_lds_dwordx4 v[186:187], off
	s_add_i32 m0, s26, 0x2000
	s_add_u32 s26, s4, 0x10000
	v_lshl_add_u64 v[222:223], s[4:5], 0, v[134:135]
	s_addc_u32 s27, s5, 0
	s_add_i32 s97, s79, s35
	global_load_lds_dwordx4 v[222:223], off
	v_lshl_add_u64 v[224:225], s[26:27], 0, v[130:131]
	s_mov_b32 m0, s97
	v_lshl_add_u64 v[226:227], s[24:25], 0, v[132:133]
	global_load_lds_dwordx4 v[224:225], off
	v_lshl_add_u64 v[224:225], s[26:27], 0, v[134:135]
	s_add_i32 m0, s97, 0x2000
	s_nop 0
	global_load_lds_dwordx4 v[224:225], off
	v_lshl_add_u64 v[224:225], s[24:25], 0, v[128:129]
	s_mov_b32 m0, s62
	s_nop 0
	global_load_lds_dwordx4 v[224:225], off
	s_mov_b32 m0, s63
	s_nop 0
	global_load_lds_dwordx4 v[226:227], off
	s_waitcnt vmcnt(8)
	s_waitcnt lgkmcnt(0)
	s_barrier
	s_waitcnt lgkmcnt(0)
	v_mfma_f32_16x16x32_bf16 v[60:63], v[154:157], v[190:193], v[60:63]
	v_mfma_f32_16x16x32_bf16 v[56:59], v[162:165], v[190:193], v[56:59]
	v_mfma_f32_16x16x32_bf16 v[44:47], v[154:157], v[198:201], v[44:47]
	v_mfma_f32_16x16x32_bf16 v[40:43], v[162:165], v[198:201], v[40:43]
	v_mfma_f32_16x16x32_bf16 v[28:31], v[154:157], v[206:209], v[28:31]
	v_mfma_f32_16x16x32_bf16 v[24:27], v[162:165], v[206:209], v[24:27]
	v_mfma_f32_16x16x32_bf16 v[12:15], v[154:157], v[214:217], v[12:15]
	v_mfma_f32_16x16x32_bf16 v[8:11], v[162:165], v[214:217], v[8:11]
	v_mfma_f32_16x16x32_bf16 v[60:63], v[158:161], v[194:197], v[60:63]
	v_mfma_f32_16x16x32_bf16 v[56:59], v[166:169], v[194:197], v[56:59]
	v_mfma_f32_16x16x32_bf16 v[44:47], v[158:161], v[202:205], v[44:47]
	v_mfma_f32_16x16x32_bf16 v[40:43], v[166:169], v[202:205], v[40:43]
	v_mfma_f32_16x16x32_bf16 v[28:31], v[158:161], v[210:213], v[28:31]
	v_mfma_f32_16x16x32_bf16 v[24:27], v[166:169], v[210:213], v[24:27]
	v_mfma_f32_16x16x32_bf16 v[12:15], v[158:161], v[218:221], v[12:15]
	v_mfma_f32_16x16x32_bf16 v[8:11], v[166:169], v[218:221], v[8:11]
	v_mfma_f32_16x16x32_bf16 v[52:55], v[170:173], v[190:193], v[52:55]
	v_mfma_f32_16x16x32_bf16 v[48:51], v[178:181], v[190:193], v[48:51]
	v_mfma_f32_16x16x32_bf16 v[36:39], v[170:173], v[198:201], v[36:39]
	v_mfma_f32_16x16x32_bf16 v[32:35], v[178:181], v[198:201], v[32:35]
	v_mfma_f32_16x16x32_bf16 v[20:23], v[170:173], v[206:209], v[20:23]
	v_mfma_f32_16x16x32_bf16 v[16:19], v[178:181], v[206:209], v[16:19]
	v_mfma_f32_16x16x32_bf16 v[4:7], v[170:173], v[214:217], v[4:7]
	v_mfma_f32_16x16x32_bf16 v[0:3], v[178:181], v[214:217], v[0:3]
	v_mfma_f32_16x16x32_bf16 v[52:55], v[174:177], v[194:197], v[52:55]
	v_mfma_f32_16x16x32_bf16 v[48:51], v[182:185], v[194:197], v[48:51]
	v_mfma_f32_16x16x32_bf16 v[36:39], v[174:177], v[202:205], v[36:39]
	v_mfma_f32_16x16x32_bf16 v[32:35], v[182:185], v[202:205], v[32:35]
	v_mfma_f32_16x16x32_bf16 v[20:23], v[174:177], v[210:213], v[20:23]
	v_mfma_f32_16x16x32_bf16 v[16:19], v[182:185], v[210:213], v[16:19]
	v_mfma_f32_16x16x32_bf16 v[4:7], v[174:177], v[218:221], v[4:7]
	v_mfma_f32_16x16x32_bf16 v[0:3], v[182:185], v[218:221], v[0:3]
	s_barrier
	s_add_i32 s26, 0, 0x18000
	s_add_i32 s27, 0, 0x1c000
	v_add_u32_e32 v166, s26, v146
	v_add_u32_e32 v182, s27, v146
	ds_read_b128 v[154:157], v166
	ds_read_b128 v[158:161], v166 offset:1024
	ds_read_b128 v[162:165], v166 offset:2048
	ds_read_b128 v[166:169], v166 offset:3072
	ds_read_b128 v[170:173], v182
	ds_read_b128 v[174:177], v182 offset:1024
	ds_read_b128 v[178:181], v182 offset:2048
	ds_read_b128 v[182:185], v182 offset:3072
	s_add_u32 s24, s24, 0x304000
	s_addc_u32 s25, s25, 0
	s_mov_b32 m0, s64
	v_lshl_add_u64 v[228:229], s[24:25], 0, v[128:129]
	ds_read_b128 v[190:193], v151 offset:32768
	ds_read_b128 v[194:197], v151 offset:33792
	ds_read_b128 v[198:201], v151 offset:34816
	ds_read_b128 v[202:205], v151 offset:35840
	ds_read_b128 v[206:209], v151 offset:36864
	ds_read_b128 v[210:213], v151 offset:37888
	ds_read_b128 v[214:217], v151 offset:38912
	ds_read_b128 v[218:221], v151 offset:39936
	global_load_lds_dwordx4 v[228:229], off
	v_lshl_add_u64 v[228:229], s[24:25], 0, v[132:133]
	s_mov_b32 m0, s65
	s_nop 0
	global_load_lds_dwordx4 v[228:229], off
	s_waitcnt vmcnt(8)
	s_waitcnt lgkmcnt(0)
	s_barrier
	s_waitcnt lgkmcnt(0)
	v_mfma_f32_16x16x32_bf16 v[124:127], v[154:157], v[190:193], v[124:127]
	v_mfma_f32_16x16x32_bf16 v[120:123], v[162:165], v[190:193], v[120:123]
	v_mfma_f32_16x16x32_bf16 v[108:111], v[154:157], v[198:201], v[108:111]
	v_mfma_f32_16x16x32_bf16 v[104:107], v[162:165], v[198:201], v[104:107]
	v_mfma_f32_16x16x32_bf16 v[92:95], v[154:157], v[206:209], v[92:95]
	v_mfma_f32_16x16x32_bf16 v[88:91], v[162:165], v[206:209], v[88:91]
	v_mfma_f32_16x16x32_bf16 v[76:79], v[154:157], v[214:217], v[76:79]
	v_mfma_f32_16x16x32_bf16 v[72:75], v[162:165], v[214:217], v[72:75]
	v_mfma_f32_16x16x32_bf16 v[124:127], v[158:161], v[194:197], v[124:127]
	v_mfma_f32_16x16x32_bf16 v[120:123], v[166:169], v[194:197], v[120:123]
	v_mfma_f32_16x16x32_bf16 v[108:111], v[158:161], v[202:205], v[108:111]
	v_mfma_f32_16x16x32_bf16 v[104:107], v[166:169], v[202:205], v[104:107]
	v_mfma_f32_16x16x32_bf16 v[92:95], v[158:161], v[210:213], v[92:95]
	v_mfma_f32_16x16x32_bf16 v[88:91], v[166:169], v[210:213], v[88:91]
	v_mfma_f32_16x16x32_bf16 v[76:79], v[158:161], v[218:221], v[76:79]
	v_mfma_f32_16x16x32_bf16 v[72:75], v[166:169], v[218:221], v[72:75]
	v_mfma_f32_16x16x32_bf16 v[116:119], v[170:173], v[190:193], v[116:119]
	v_mfma_f32_16x16x32_bf16 v[112:115], v[178:181], v[190:193], v[112:115]
	v_mfma_f32_16x16x32_bf16 v[100:103], v[170:173], v[198:201], v[100:103]
	v_mfma_f32_16x16x32_bf16 v[96:99], v[178:181], v[198:201], v[96:99]
	v_mfma_f32_16x16x32_bf16 v[84:87], v[170:173], v[206:209], v[84:87]
	v_mfma_f32_16x16x32_bf16 v[80:83], v[178:181], v[206:209], v[80:83]
	v_mfma_f32_16x16x32_bf16 v[68:71], v[170:173], v[214:217], v[68:71]
	v_mfma_f32_16x16x32_bf16 v[64:67], v[178:181], v[214:217], v[64:67]
	v_mfma_f32_16x16x32_bf16 v[116:119], v[174:177], v[194:197], v[116:119]
	v_mfma_f32_16x16x32_bf16 v[112:115], v[182:185], v[194:197], v[112:115]
	v_mfma_f32_16x16x32_bf16 v[100:103], v[174:177], v[202:205], v[100:103]
	v_mfma_f32_16x16x32_bf16 v[96:99], v[182:185], v[202:205], v[96:99]
	v_mfma_f32_16x16x32_bf16 v[84:87], v[174:177], v[210:213], v[84:87]
	v_mfma_f32_16x16x32_bf16 v[80:83], v[182:185], v[210:213], v[80:83]
	v_mfma_f32_16x16x32_bf16 v[68:71], v[174:177], v[218:221], v[68:71]
	v_mfma_f32_16x16x32_bf16 v[64:67], v[182:185], v[218:221], v[64:67]
	s_barrier
	s_add_i32 s24, s26, s35
	v_lshl_add_u64 v[186:187], v[186:187], 0, s[8:9]
	s_mov_b32 m0, s24
	ds_read_b128 v[190:193], v151 offset:49152
	ds_read_b128 v[194:197], v151 offset:50176
	ds_read_b128 v[198:201], v151 offset:51200
	ds_read_b128 v[202:205], v151 offset:52224
	ds_read_b128 v[206:209], v151 offset:53248
	ds_read_b128 v[210:213], v151 offset:54272
	ds_read_b128 v[214:217], v151 offset:55296
	ds_read_b128 v[218:221], v151 offset:56320
	global_load_lds_dwordx4 v[186:187], off
	s_add_i32 m0, s24, 0x2000
	s_add_u32 s4, s4, 0x10080
	v_lshl_add_u64 v[186:187], v[222:223], 0, s[8:9]
	s_addc_u32 s5, s5, 0
	s_add_i32 s24, s27, s35
	global_load_lds_dwordx4 v[186:187], off
	v_lshl_add_u64 v[186:187], s[4:5], 0, v[130:131]
	s_mov_b32 m0, s24
	s_nop 0
	global_load_lds_dwordx4 v[186:187], off
	v_lshl_add_u64 v[186:187], s[4:5], 0, v[134:135]
	s_add_i32 m0, s24, 0x2000
	s_nop 0
	global_load_lds_dwordx4 v[186:187], off
	v_lshl_add_u64 v[186:187], v[224:225], 0, s[8:9]
	s_mov_b32 m0, s66
	s_nop 0
	global_load_lds_dwordx4 v[186:187], off
	v_lshl_add_u64 v[186:187], v[226:227], 0, s[8:9]
	s_mov_b32 m0, s67
	s_nop 0
	global_load_lds_dwordx4 v[186:187], off
	s_waitcnt vmcnt(8)
	s_waitcnt lgkmcnt(0)
	s_barrier
	s_waitcnt lgkmcnt(0)
	v_mfma_f32_16x16x32_bf16 v[60:63], v[154:157], v[190:193], v[60:63]
	v_mfma_f32_16x16x32_bf16 v[56:59], v[162:165], v[190:193], v[56:59]
	v_mfma_f32_16x16x32_bf16 v[44:47], v[154:157], v[198:201], v[44:47]
	v_mfma_f32_16x16x32_bf16 v[40:43], v[162:165], v[198:201], v[40:43]
	v_mfma_f32_16x16x32_bf16 v[28:31], v[154:157], v[206:209], v[28:31]
	v_mfma_f32_16x16x32_bf16 v[24:27], v[162:165], v[206:209], v[24:27]
	v_mfma_f32_16x16x32_bf16 v[12:15], v[154:157], v[214:217], v[12:15]
	v_mfma_f32_16x16x32_bf16 v[8:11], v[162:165], v[214:217], v[8:11]
	v_mfma_f32_16x16x32_bf16 v[60:63], v[158:161], v[194:197], v[60:63]
	v_mfma_f32_16x16x32_bf16 v[56:59], v[166:169], v[194:197], v[56:59]
	v_mfma_f32_16x16x32_bf16 v[44:47], v[158:161], v[202:205], v[44:47]
	v_mfma_f32_16x16x32_bf16 v[40:43], v[166:169], v[202:205], v[40:43]
	v_mfma_f32_16x16x32_bf16 v[28:31], v[158:161], v[210:213], v[28:31]
	v_mfma_f32_16x16x32_bf16 v[24:27], v[166:169], v[210:213], v[24:27]
	v_mfma_f32_16x16x32_bf16 v[12:15], v[158:161], v[218:221], v[12:15]
	v_mfma_f32_16x16x32_bf16 v[8:11], v[166:169], v[218:221], v[8:11]
	v_mfma_f32_16x16x32_bf16 v[52:55], v[170:173], v[190:193], v[52:55]
	v_mfma_f32_16x16x32_bf16 v[48:51], v[178:181], v[190:193], v[48:51]
	v_mfma_f32_16x16x32_bf16 v[36:39], v[170:173], v[198:201], v[36:39]
	v_mfma_f32_16x16x32_bf16 v[32:35], v[178:181], v[198:201], v[32:35]
	v_mfma_f32_16x16x32_bf16 v[20:23], v[170:173], v[206:209], v[20:23]
	v_mfma_f32_16x16x32_bf16 v[16:19], v[178:181], v[206:209], v[16:19]
	v_mfma_f32_16x16x32_bf16 v[4:7], v[170:173], v[214:217], v[4:7]
	v_mfma_f32_16x16x32_bf16 v[0:3], v[178:181], v[214:217], v[0:3]
	v_mfma_f32_16x16x32_bf16 v[52:55], v[174:177], v[194:197], v[52:55]
	v_mfma_f32_16x16x32_bf16 v[48:51], v[182:185], v[194:197], v[48:51]
	v_mfma_f32_16x16x32_bf16 v[36:39], v[174:177], v[202:205], v[36:39]
	v_mfma_f32_16x16x32_bf16 v[32:35], v[182:185], v[202:205], v[32:35]
	v_mfma_f32_16x16x32_bf16 v[20:23], v[174:177], v[210:213], v[20:23]
	v_mfma_f32_16x16x32_bf16 v[16:19], v[182:185], v[210:213], v[16:19]
	v_mfma_f32_16x16x32_bf16 v[4:7], v[174:177], v[218:221], v[4:7]
	v_mfma_f32_16x16x32_bf16 v[0:3], v[182:185], v[218:221], v[0:3]
	s_barrier
	s_add_i32 s96, s96, 4
	s_and_b32 s4, s96, 6
	s_cmp_eq_u32 s4, 0
	s_cselect_b64 s[4:5], -1, 0
	s_cmp_lt_u32 s95, 38
	s_cselect_b64 s[24:25], -1, 0
	s_and_b64 s[4:5], s[4:5], s[24:25]
	s_andn2_b64 vcc, exec, s[4:5]
	s_cbranch_vccnz .LBB0_407
	v_add_u32_e32 v154, s94, v148
	v_add_u32_e32 v155, 0x26500, v154
	v_add_u32_e32 v156, 0x26540, v154
	v_add_u32_e32 v157, 0x26580, v154
	v_add_u32_e32 v159, 0x265c0, v154
	v_add_u32_e32 v161, 0x26700, v154
	v_add_u32_e32 v163, 0x26740, v154
	v_add_u32_e32 v165, 0x26780, v154
	v_add_u32_e32 v167, 0x267c0, v154
	ds_read_b32 v154, v155
	ds_read_b32 v156, v156
	ds_read_b32 v158, v157
	ds_read_b32 v160, v159
	ds_read_b32 v162, v161
	ds_read_b32 v164, v163
	ds_read_b32 v166, v165
	ds_read_b32 v168, v167
	s_waitcnt lgkmcnt(0)
	v_pk_mul_f32 v[126:127], v[126:127], v[154:155] op_sel_hi:[1,0]
	v_pk_mul_f32 v[124:125], v[124:125], v[154:155] op_sel_hi:[1,0]
	v_pk_mul_f32 v[122:123], v[122:123], v[154:155] op_sel_hi:[1,0]
	v_pk_mul_f32 v[120:121], v[120:121], v[154:155] op_sel_hi:[1,0]
	v_pk_mul_f32 v[118:119], v[118:119], v[154:155] op_sel_hi:[1,0]
	v_pk_mul_f32 v[116:117], v[116:117], v[154:155] op_sel_hi:[1,0]
	v_pk_mul_f32 v[114:115], v[114:115], v[154:155] op_sel_hi:[1,0]
	v_pk_mul_f32 v[112:113], v[112:113], v[154:155] op_sel_hi:[1,0]
	v_pk_mul_f32 v[110:111], v[110:111], v[156:157] op_sel_hi:[1,0]
	v_pk_mul_f32 v[108:109], v[108:109], v[156:157] op_sel_hi:[1,0]
	v_pk_mul_f32 v[106:107], v[106:107], v[156:157] op_sel_hi:[1,0]
	v_pk_mul_f32 v[104:105], v[104:105], v[156:157] op_sel_hi:[1,0]
	v_pk_mul_f32 v[102:103], v[102:103], v[156:157] op_sel_hi:[1,0]
	v_pk_mul_f32 v[100:101], v[100:101], v[156:157] op_sel_hi:[1,0]
	v_pk_mul_f32 v[98:99], v[98:99], v[156:157] op_sel_hi:[1,0]
	v_pk_mul_f32 v[96:97], v[96:97], v[156:157] op_sel_hi:[1,0]
	v_pk_mul_f32 v[94:95], v[94:95], v[158:159] op_sel_hi:[1,0]
	v_pk_mul_f32 v[92:93], v[92:93], v[158:159] op_sel_hi:[1,0]
	v_pk_mul_f32 v[90:91], v[90:91], v[158:159] op_sel_hi:[1,0]
	v_pk_mul_f32 v[88:89], v[88:89], v[158:159] op_sel_hi:[1,0]
	v_pk_mul_f32 v[86:87], v[86:87], v[158:159] op_sel_hi:[1,0]
	v_pk_mul_f32 v[84:85], v[84:85], v[158:159] op_sel_hi:[1,0]
	v_pk_mul_f32 v[82:83], v[82:83], v[158:159] op_sel_hi:[1,0]
	v_pk_mul_f32 v[80:81], v[80:81], v[158:159] op_sel_hi:[1,0]
	v_pk_mul_f32 v[78:79], v[78:79], v[160:161] op_sel_hi:[1,0]
	v_pk_mul_f32 v[76:77], v[76:77], v[160:161] op_sel_hi:[1,0]
	v_pk_mul_f32 v[74:75], v[74:75], v[160:161] op_sel_hi:[1,0]
	v_pk_mul_f32 v[72:73], v[72:73], v[160:161] op_sel_hi:[1,0]
	v_pk_mul_f32 v[70:71], v[70:71], v[160:161] op_sel_hi:[1,0]
	v_pk_mul_f32 v[68:69], v[68:69], v[160:161] op_sel_hi:[1,0]
	v_pk_mul_f32 v[66:67], v[66:67], v[160:161] op_sel_hi:[1,0]
	v_pk_mul_f32 v[64:65], v[64:65], v[160:161] op_sel_hi:[1,0]
	v_pk_mul_f32 v[62:63], v[62:63], v[162:163] op_sel_hi:[1,0]
	v_pk_mul_f32 v[60:61], v[60:61], v[162:163] op_sel_hi:[1,0]
	v_pk_mul_f32 v[58:59], v[58:59], v[162:163] op_sel_hi:[1,0]
	v_pk_mul_f32 v[56:57], v[56:57], v[162:163] op_sel_hi:[1,0]
	v_pk_mul_f32 v[54:55], v[54:55], v[162:163] op_sel_hi:[1,0]
	v_pk_mul_f32 v[52:53], v[52:53], v[162:163] op_sel_hi:[1,0]
	v_pk_mul_f32 v[50:51], v[50:51], v[162:163] op_sel_hi:[1,0]
	v_pk_mul_f32 v[48:49], v[48:49], v[162:163] op_sel_hi:[1,0]
	v_pk_mul_f32 v[46:47], v[46:47], v[164:165] op_sel_hi:[1,0]
	v_pk_mul_f32 v[44:45], v[44:45], v[164:165] op_sel_hi:[1,0]
	v_pk_mul_f32 v[42:43], v[42:43], v[164:165] op_sel_hi:[1,0]
	v_pk_mul_f32 v[40:41], v[40:41], v[164:165] op_sel_hi:[1,0]
	v_pk_mul_f32 v[38:39], v[38:39], v[164:165] op_sel_hi:[1,0]
	v_pk_mul_f32 v[36:37], v[36:37], v[164:165] op_sel_hi:[1,0]
	v_pk_mul_f32 v[34:35], v[34:35], v[164:165] op_sel_hi:[1,0]
	v_pk_mul_f32 v[32:33], v[32:33], v[164:165] op_sel_hi:[1,0]
	v_pk_mul_f32 v[30:31], v[30:31], v[166:167] op_sel_hi:[1,0]
	v_pk_mul_f32 v[28:29], v[28:29], v[166:167] op_sel_hi:[1,0]
	v_pk_mul_f32 v[26:27], v[26:27], v[166:167] op_sel_hi:[1,0]
	v_pk_mul_f32 v[24:25], v[24:25], v[166:167] op_sel_hi:[1,0]
	v_pk_mul_f32 v[22:23], v[22:23], v[166:167] op_sel_hi:[1,0]
	v_pk_mul_f32 v[20:21], v[20:21], v[166:167] op_sel_hi:[1,0]
	v_pk_mul_f32 v[18:19], v[18:19], v[166:167] op_sel_hi:[1,0]
	v_pk_mul_f32 v[16:17], v[16:17], v[166:167] op_sel_hi:[1,0]
	v_pk_mul_f32 v[14:15], v[14:15], v[168:169] op_sel_hi:[1,0]
	v_pk_mul_f32 v[12:13], v[12:13], v[168:169] op_sel_hi:[1,0]
	v_pk_mul_f32 v[10:11], v[10:11], v[168:169] op_sel_hi:[1,0]
	v_pk_mul_f32 v[8:9], v[8:9], v[168:169] op_sel_hi:[1,0]
	v_pk_mul_f32 v[6:7], v[6:7], v[168:169] op_sel_hi:[1,0]
	v_pk_mul_f32 v[4:5], v[4:5], v[168:169] op_sel_hi:[1,0]
	v_pk_mul_f32 v[2:3], v[2:3], v[168:169] op_sel_hi:[1,0]
	v_pk_mul_f32 v[0:1], v[0:1], v[168:169] op_sel_hi:[1,0]
	s_branch .LBB0_407

.LBB0_416:
	s_waitcnt vmcnt(0)
	s_waitcnt vmcnt(0)
	s_setprio 0
	s_barrier
	s_and_saveexec_b64 s[0:1], s[28:29]
	s_cbranch_execz .LBB0_468
	s_add_i32 s2, 0, 0x24800
	v_mov_b32_e32 v0, s2
	s_waitcnt vmcnt(0) expcnt(0) lgkmcnt(0)
	ds_read_b32 v2, v0
	s_add_i32 s2, 0, 0x24804
	v_mov_b32_e32 v0, s2
	ds_read_b32 v0, v0
	s_waitcnt lgkmcnt(1)
	v_cmp_ne_u32_e32 vcc, 0, v2
	s_cbranch_vccnz .LBB0_432
	v_readlane_b32 s2, v253, 0
	s_mul_i32 s16, s69, s2
	s_add_u32 s2, s50, 0x1000
	s_addc_u32 s3, s51, 0
	s_add_u32 s4, s50, 0x1100
	s_addc_u32 s5, s51, 0
	s_add_u32 s6, s50, 0x1200
	s_addc_u32 s7, s51, 0
	s_add_u32 s8, s50, 0x1300
	s_mul_i32 s16, s16, s68
	s_addc_u32 s9, s51, 0
	s_mov_b32 s17, 1
	v_mov_b32_e32 v16, 0
	s_branch .LBB0_420

.LBB0_536:
	v_readlane_b32 s2, v253, 1
	v_mov_b32_e32 v9, v188
	v_readlane_b32 s3, v253, 2
	s_andn2_b64 vcc, exec, s[2:3]
	v_readfirstlane_b32 s4, v9
	s_cbranch_vccnz .LBB0_552
	v_lshlrev_b32_e32 v0, 4, v9
	v_add_u32_e32 v1, 0x2000, v0
	v_ashrrev_i32_e32 v2, 31, v1
	v_lshrrev_b32_e32 v2, 22, v2
	v_add_u32_e32 v2, v1, v2
	v_ashrrev_i32_e32 v8, 10, v2
	v_mul_i32_i24_e32 v2, 0x400, v8
	v_sub_u32_e32 v1, v1, v2
	v_lshrrev_b32_e32 v2, 4, v1
	v_bitop3_b32 v1, v2, v1, 32 bitop3:0x6c
	v_ashrrev_i32_e32 v2, 31, v1
	v_lshrrev_b32_e32 v2, 26, v2
	v_add_u32_e32 v2, v1, v2
	v_lshlrev_b32_e32 v3, 3, v8
	v_ashrrev_i32_e32 v10, 6, v2
	v_and_b32_e32 v3, -16, v3
	v_add_u32_e32 v3, v10, v3
	v_lshlrev_b32_e32 v4, 2, v3
	v_and_b32_e32 v5, 3, v10
	s_lshr_b32 s2, s87, 29
	v_and_or_b32 v4, v4, 48, v5
	v_lshlrev_b32_e32 v5, 1, v3
	v_lshrrev_b32_e32 v6, 2, v3
	v_and_b32_e32 v2, 0xc0, v2
	s_add_i32 s2, s30, s2
	s_ashr_i32 s8, s4, 6
	v_and_b32_e32 v5, 0xfffc0, v5
	v_and_b32_e32 v6, 4, v6
	v_sub_u32_e32 v1, v1, v2
	v_mov_b32_e32 v2, 1
	s_ashr_i32 s5, s2, 3
	s_and_b32 s2, s2, -8
	s_ashr_i32 s3, s4, 8
	s_lshl_b32 s35, s8, 10
	v_or3_b32 v4, v4, v5, v6
	v_lshlrev_b32_e32 v5, 5, v8
	v_ashrrev_i16_sdwa v1, v2, sext(v1) dst_sel:DWORD dst_unused:UNUSED_PAD src0_sel:DWORD src1_sel:BYTE_0
	s_sub_i32 s2, s30, s2
	v_and_b32_e32 v5, 32, v5
	v_bfe_i32 v11, v1, 0, 16
	s_cmp_lt_i32 s2, 0
	s_movk_i32 s36, 0x181
	v_add_lshl_u32 v1, v5, v11, 1
	s_cselect_b32 s6, s36, 0x180
	v_lshl_add_u32 v128, v4, 12, v1
	v_lshl_add_u32 v130, v3, 12, v1
	v_bfe_i32 v1, v9, 27, 1
	s_mul_i32 s2, s2, s6
	v_lshrrev_b32_e32 v1, 22, v1
	s_add_i32 s2, s2, s5
	v_add_u32_e32 v1, v0, v1
	s_mul_hi_i32 s5, s2, 0x2aaaaaab
	v_and_b32_e32 v1, 0xfffffc00, v1
	s_lshr_b32 s6, s5, 31
	s_ashr_i32 s5, s5, 6
	v_sub_u32_e32 v0, v0, v1
	s_add_i32 s5, s5, s6
	v_lshrrev_b32_e32 v1, 4, v0
	v_ashrrev_i32_e32 v3, 31, v9
	s_lshl_b32 s6, s5, 3
	s_mulk_i32 s5, 0x180
	v_bitop3_b32 v0, v1, v0, 32 bitop3:0x6c
	v_lshrrev_b32_e32 v3, 26, v3
	s_sub_i32 s5, s2, s5
	v_ashrrev_i32_e32 v1, 31, v0
	v_add_u32_e32 v3, v9, v3
	s_sext_i32_i16 s2, s5
	v_lshrrev_b32_e32 v1, 26, v1
	v_ashrrev_i32_e32 v13, 6, v3
	s_bfe_u32 s2, s2, 0x3001c
	v_add_u32_e32 v1, v0, v1
	v_lshlrev_b32_e32 v3, 3, v13
	s_add_i32 s7, s5, s2
	v_ashrrev_i32_e32 v12, 6, v1
	v_and_b32_e32 v3, -16, v3
	s_sext_i32_i16 s2, s7
	s_and_b32 s7, s7, 0xfff8
	v_add_u32_e32 v3, v12, v3
	s_sub_i32 s5, s5, s7
	v_lshlrev_b32_e32 v4, 2, v3
	v_and_b32_e32 v5, 3, v12
	s_sext_i32_i16 s5, s5
	v_and_or_b32 v4, v4, 48, v5
	v_lshlrev_b32_e32 v5, 1, v3
	v_lshrrev_b32_e32 v6, 2, v3
	v_and_b32_e32 v1, 0xc0, v1
	s_lshr_b32 s2, s2, 3
	s_add_i32 s18, s6, s5
	v_and_b32_e32 v5, 0xfffc0, v5
	v_and_b32_e32 v6, 4, v6
	v_sub_u32_e32 v0, v0, v1
	s_ashr_i32 s19, s18, 31
	s_bfe_i64 s[10:11], s[2:3], 0x100000
	v_or3_b32 v4, v4, v5, v6
	v_lshlrev_b32_e32 v5, 5, v13
	v_ashrrev_i16_sdwa v0, v2, sext(v0) dst_sel:DWORD dst_unused:UNUSED_PAD src0_sel:DWORD src1_sel:BYTE_0
	s_lshl_b64 s[6:7], s[18:19], 20
	s_lshl_b64 s[10:11], s[10:11], 20
	v_and_b32_e32 v5, 32, v5
	v_bfe_i32 v14, v0, 0, 16
	s_add_u32 s24, s70, s10
	v_add_lshl_u32 v0, v5, v14, 1
	s_addc_u32 s25, s71, s11
	s_add_i32 s19, s35, 0
	v_lshl_add_u32 v132, v4, 12, v0
	s_add_i32 m0, s19, 0x10000
	v_lshl_add_u32 v134, v3, 12, v0
	global_load_lds_dwordx4 v132, s[24:25]
	s_add_i32 m0, s19, 0x12000
	s_add_u32 s10, s24, 0x8000
	global_load_lds_dwordx4 v128, s[24:25]
	s_addc_u32 s11, s25, 0
	s_add_i32 m0, s19, 0x14000
	v_mov_b32_e32 v137, 0
	global_load_lds_dwordx4 v132, s[10:11]
	s_add_i32 m0, s19, 0x16000
	s_add_u32 s22, s58, s6
	s_addc_u32 s23, s59, s7
	s_add_i32 s37, s19, 0x2000
	global_load_lds_dwordx4 v128, s[10:11]
	s_mov_b32 m0, s19
	s_add_u32 s6, s22, 0x80000
	global_load_lds_dwordx4 v134, s[22:23]
	s_mov_b32 m0, s37
	s_addc_u32 s7, s23, 0
	s_add_i32 s38, s19, 0x4000
	global_load_lds_dwordx4 v130, s[22:23]
	s_mov_b32 m0, s38
	s_add_i32 s39, s19, 0x6000
	global_load_lds_dwordx4 v134, s[6:7]
	s_mov_b32 m0, s39
	v_mov_b32_e32 v133, v137
	global_load_lds_dwordx4 v130, s[6:7]
	v_mov_b32_e32 v129, v137
	v_mov_b32_e32 v135, v137
	v_mov_b32_e32 v131, v137
	s_cmp_eq_u32 s3, 1
	s_mov_b32 s5, 0
	v_lshl_add_u64 v[6:7], s[24:25], 0, v[132:133]
	v_lshl_add_u64 v[4:5], s[24:25], 0, v[128:129]
	v_lshl_add_u64 v[0:1], s[22:23], 0, v[134:135]
	s_cselect_b64 s[6:7], -1, 0
	s_cmp_lg_u32 s3, 1
	v_lshl_add_u64 v[2:3], s[22:23], 0, v[130:131]
	s_cbranch_scc1 .LBB0_539
	s_barrier
	s_setprio 1

.LBB0_545:
	ds_read_b128 v[154:157], v148
	ds_read_b128 v[158:161], v148 offset:1024
	ds_read_b128 v[162:165], v148 offset:2048
	ds_read_b128 v[166:169], v148 offset:3072
	ds_read_b128 v[170:173], v149
	ds_read_b128 v[174:177], v149 offset:1024
	ds_read_b128 v[178:181], v149 offset:2048
	ds_read_b128 v[182:185], v149 offset:3072
	s_add_u32 s24, s22, 0xfff80080
	s_addc_u32 s25, s23, -1
	s_cmp_eq_u32 s86, 28
	s_cselect_b32 s27, s15, s25
	s_cselect_b32 s26, s95, s24
	s_cselect_b32 s25, s13, vcc_lo
	s_cselect_b32 s24, s96, s97
	v_lshl_add_u64 v[186:187], s[22:23], 0, v[138:139]
	s_add_i32 m0, s19, 0xc000
	ds_read_b128 v[190:193], v150
	ds_read_b128 v[194:197], v150 offset:1024
	ds_read_b128 v[198:201], v150 offset:2048
	ds_read_b128 v[202:205], v150 offset:3072
	ds_read_b128 v[206:209], v150 offset:4096
	ds_read_b128 v[210:213], v150 offset:5120
	ds_read_b128 v[214:217], v150 offset:6144
	ds_read_b128 v[218:221], v150 offset:7168
	global_load_lds_dwordx4 v[186:187], off
	v_lshl_add_u64 v[186:187], s[22:23], 0, v[140:141]
	s_add_i32 m0, s19, 0xe000
	s_nop 0
	global_load_lds_dwordx4 v[186:187], off
	s_waitcnt vmcnt(8)
	s_waitcnt lgkmcnt(0)
	s_barrier
	s_waitcnt lgkmcnt(0)
	v_mfma_f32_16x16x32_bf16 v[124:127], v[154:157], v[190:193], v[124:127]
	v_mfma_f32_16x16x32_bf16 v[120:123], v[162:165], v[190:193], v[120:123]
	v_mfma_f32_16x16x32_bf16 v[116:119], v[154:157], v[198:201], v[116:119]
	v_mfma_f32_16x16x32_bf16 v[108:111], v[162:165], v[198:201], v[108:111]
	v_mfma_f32_16x16x32_bf16 v[100:103], v[154:157], v[206:209], v[100:103]
	v_mfma_f32_16x16x32_bf16 v[92:95], v[162:165], v[206:209], v[92:95]
	v_mfma_f32_16x16x32_bf16 v[84:87], v[154:157], v[214:217], v[84:87]
	v_mfma_f32_16x16x32_bf16 v[76:79], v[162:165], v[214:217], v[76:79]
	v_mfma_f32_16x16x32_bf16 v[124:127], v[158:161], v[194:197], v[124:127]
	v_mfma_f32_16x16x32_bf16 v[120:123], v[166:169], v[194:197], v[120:123]
	v_mfma_f32_16x16x32_bf16 v[116:119], v[158:161], v[202:205], v[116:119]
	v_mfma_f32_16x16x32_bf16 v[108:111], v[166:169], v[202:205], v[108:111]
	v_mfma_f32_16x16x32_bf16 v[100:103], v[158:161], v[210:213], v[100:103]
	v_mfma_f32_16x16x32_bf16 v[92:95], v[166:169], v[210:213], v[92:95]
	v_mfma_f32_16x16x32_bf16 v[84:87], v[158:161], v[218:221], v[84:87]
	v_mfma_f32_16x16x32_bf16 v[76:79], v[166:169], v[218:221], v[76:79]
	v_mfma_f32_16x16x32_bf16 v[112:115], v[170:173], v[190:193], v[112:115]
	v_mfma_f32_16x16x32_bf16 v[104:107], v[178:181], v[190:193], v[104:107]
	v_mfma_f32_16x16x32_bf16 v[96:99], v[170:173], v[198:201], v[96:99]
	v_mfma_f32_16x16x32_bf16 v[88:91], v[178:181], v[198:201], v[88:91]
	v_mfma_f32_16x16x32_bf16 v[80:83], v[170:173], v[206:209], v[80:83]
	v_mfma_f32_16x16x32_bf16 v[72:75], v[178:181], v[206:209], v[72:75]
	v_mfma_f32_16x16x32_bf16 v[68:71], v[170:173], v[214:217], v[68:71]
	v_mfma_f32_16x16x32_bf16 v[64:67], v[178:181], v[214:217], v[64:67]
	v_mfma_f32_16x16x32_bf16 v[112:115], v[174:177], v[194:197], v[112:115]
	v_mfma_f32_16x16x32_bf16 v[104:107], v[182:185], v[194:197], v[104:107]
	v_mfma_f32_16x16x32_bf16 v[96:99], v[174:177], v[202:205], v[96:99]
	v_mfma_f32_16x16x32_bf16 v[88:91], v[182:185], v[202:205], v[88:91]
	v_mfma_f32_16x16x32_bf16 v[80:83], v[174:177], v[210:213], v[80:83]
	v_mfma_f32_16x16x32_bf16 v[72:75], v[182:185], v[210:213], v[72:75]
	v_mfma_f32_16x16x32_bf16 v[68:71], v[174:177], v[218:221], v[68:71]
	v_mfma_f32_16x16x32_bf16 v[64:67], v[182:185], v[218:221], v[64:67]
	s_barrier
	s_add_i32 s74, s64, s35
	v_lshl_add_u64 v[186:187], s[24:25], 0, v[132:133]
	s_mov_b32 m0, s74
	ds_read_b128 v[190:193], v150 offset:16384
	ds_read_b128 v[194:197], v150 offset:17408
	ds_read_b128 v[198:201], v150 offset:18432
	ds_read_b128 v[202:205], v150 offset:19456
	ds_read_b128 v[206:209], v150 offset:20480
	ds_read_b128 v[210:213], v150 offset:21504
	ds_read_b128 v[214:217], v150 offset:22528
	ds_read_b128 v[218:221], v150 offset:23552
	global_load_lds_dwordx4 v[186:187], off
	s_add_i32 m0, s74, 0x2000
	s_add_u32 s74, s24, 0x8000
	v_lshl_add_u64 v[222:223], s[24:25], 0, v[128:129]
	s_addc_u32 s75, s25, 0
	s_add_i32 vcc_hi, s65, s35
	global_load_lds_dwordx4 v[222:223], off
	v_lshl_add_u64 v[224:225], s[74:75], 0, v[132:133]
	s_mov_b32 m0, vcc_hi
	v_lshl_add_u64 v[226:227], s[26:27], 0, v[130:131]
	global_load_lds_dwordx4 v[224:225], off
	v_lshl_add_u64 v[224:225], s[74:75], 0, v[128:129]
	s_add_i32 m0, vcc_hi, 0x2000
	s_nop 0
	global_load_lds_dwordx4 v[224:225], off
	v_lshl_add_u64 v[224:225], s[26:27], 0, v[134:135]
	s_mov_b32 m0, s19
	s_nop 0
	global_load_lds_dwordx4 v[224:225], off
	s_mov_b32 m0, s37
	s_nop 0
	global_load_lds_dwordx4 v[226:227], off
	s_waitcnt vmcnt(8)
	s_waitcnt lgkmcnt(0)
	s_barrier
	s_waitcnt lgkmcnt(0)
	v_mfma_f32_16x16x32_bf16 v[60:63], v[154:157], v[190:193], v[60:63]
	v_mfma_f32_16x16x32_bf16 v[56:59], v[162:165], v[190:193], v[56:59]
	v_mfma_f32_16x16x32_bf16 v[52:55], v[154:157], v[198:201], v[52:55]
	v_mfma_f32_16x16x32_bf16 v[44:47], v[162:165], v[198:201], v[44:47]
	v_mfma_f32_16x16x32_bf16 v[36:39], v[154:157], v[206:209], v[36:39]
	v_mfma_f32_16x16x32_bf16 v[28:31], v[162:165], v[206:209], v[28:31]
	v_mfma_f32_16x16x32_bf16 v[20:23], v[154:157], v[214:217], v[20:23]
	v_mfma_f32_16x16x32_bf16 v[12:15], v[162:165], v[214:217], v[12:15]
	v_mfma_f32_16x16x32_bf16 v[60:63], v[158:161], v[194:197], v[60:63]
	v_mfma_f32_16x16x32_bf16 v[56:59], v[166:169], v[194:197], v[56:59]
	v_mfma_f32_16x16x32_bf16 v[52:55], v[158:161], v[202:205], v[52:55]
	v_mfma_f32_16x16x32_bf16 v[44:47], v[166:169], v[202:205], v[44:47]
	v_mfma_f32_16x16x32_bf16 v[36:39], v[158:161], v[210:213], v[36:39]
	v_mfma_f32_16x16x32_bf16 v[28:31], v[166:169], v[210:213], v[28:31]
	v_mfma_f32_16x16x32_bf16 v[20:23], v[158:161], v[218:221], v[20:23]
	v_mfma_f32_16x16x32_bf16 v[12:15], v[166:169], v[218:221], v[12:15]
	v_mfma_f32_16x16x32_bf16 v[48:51], v[170:173], v[190:193], v[48:51]
	v_mfma_f32_16x16x32_bf16 v[40:43], v[178:181], v[190:193], v[40:43]
	v_mfma_f32_16x16x32_bf16 v[32:35], v[170:173], v[198:201], v[32:35]
	v_mfma_f32_16x16x32_bf16 v[24:27], v[178:181], v[198:201], v[24:27]
	v_mfma_f32_16x16x32_bf16 v[16:19], v[170:173], v[206:209], v[16:19]
	v_mfma_f32_16x16x32_bf16 v[8:11], v[178:181], v[206:209], v[8:11]
	v_mfma_f32_16x16x32_bf16 v[4:7], v[170:173], v[214:217], v[4:7]
	v_mfma_f32_16x16x32_bf16 v[0:3], v[178:181], v[214:217], v[0:3]
	v_mfma_f32_16x16x32_bf16 v[48:51], v[174:177], v[194:197], v[48:51]
	v_mfma_f32_16x16x32_bf16 v[40:43], v[182:185], v[194:197], v[40:43]
	v_mfma_f32_16x16x32_bf16 v[32:35], v[174:177], v[202:205], v[32:35]
	v_mfma_f32_16x16x32_bf16 v[24:27], v[182:185], v[202:205], v[24:27]
	v_mfma_f32_16x16x32_bf16 v[16:19], v[174:177], v[210:213], v[16:19]
	v_mfma_f32_16x16x32_bf16 v[8:11], v[182:185], v[210:213], v[8:11]
	v_mfma_f32_16x16x32_bf16 v[4:7], v[174:177], v[218:221], v[4:7]
	v_mfma_f32_16x16x32_bf16 v[0:3], v[182:185], v[218:221], v[0:3]
	s_barrier
	s_add_i32 s74, 0, 0x18000
	v_add_u32_e32 v153, s74, v146
	s_add_i32 s75, 0, 0x1c000
	ds_read_b128 v[154:157], v153
	ds_read_b128 v[158:161], v153 offset:1024
	ds_read_b128 v[162:165], v153 offset:2048
	ds_read_b128 v[166:169], v153 offset:3072
	v_add_u32_e32 v153, s75, v146
	ds_read_b128 v[170:173], v153
	ds_read_b128 v[174:177], v153 offset:1024
	ds_read_b128 v[178:181], v153 offset:2048
	ds_read_b128 v[182:185], v153 offset:3072
	s_add_u32 s26, s26, 0x80000
	s_addc_u32 s27, s27, 0
	s_mov_b32 m0, s38
	v_lshl_add_u64 v[228:229], s[26:27], 0, v[134:135]
	ds_read_b128 v[190:193], v150 offset:32768
	ds_read_b128 v[194:197], v150 offset:33792
	ds_read_b128 v[198:201], v150 offset:34816
	ds_read_b128 v[202:205], v150 offset:35840
	ds_read_b128 v[206:209], v150 offset:36864
	ds_read_b128 v[210:213], v150 offset:37888
	ds_read_b128 v[214:217], v150 offset:38912
	ds_read_b128 v[218:221], v150 offset:39936
	global_load_lds_dwordx4 v[228:229], off
	v_lshl_add_u64 v[228:229], s[26:27], 0, v[130:131]
	s_mov_b32 m0, s39
	s_nop 0
	global_load_lds_dwordx4 v[228:229], off
	s_waitcnt vmcnt(8)
	s_waitcnt lgkmcnt(0)
	s_barrier
	s_waitcnt lgkmcnt(0)
	v_mfma_f32_16x16x32_bf16 v[124:127], v[154:157], v[190:193], v[124:127]
	v_mfma_f32_16x16x32_bf16 v[120:123], v[162:165], v[190:193], v[120:123]
	v_mfma_f32_16x16x32_bf16 v[116:119], v[154:157], v[198:201], v[116:119]
	v_mfma_f32_16x16x32_bf16 v[108:111], v[162:165], v[198:201], v[108:111]
	v_mfma_f32_16x16x32_bf16 v[100:103], v[154:157], v[206:209], v[100:103]
	v_mfma_f32_16x16x32_bf16 v[92:95], v[162:165], v[206:209], v[92:95]
	v_mfma_f32_16x16x32_bf16 v[84:87], v[154:157], v[214:217], v[84:87]
	v_mfma_f32_16x16x32_bf16 v[76:79], v[162:165], v[214:217], v[76:79]
	v_mfma_f32_16x16x32_bf16 v[124:127], v[158:161], v[194:197], v[124:127]
	v_mfma_f32_16x16x32_bf16 v[120:123], v[166:169], v[194:197], v[120:123]
	v_mfma_f32_16x16x32_bf16 v[116:119], v[158:161], v[202:205], v[116:119]
	v_mfma_f32_16x16x32_bf16 v[108:111], v[166:169], v[202:205], v[108:111]
	v_mfma_f32_16x16x32_bf16 v[100:103], v[158:161], v[210:213], v[100:103]
	v_mfma_f32_16x16x32_bf16 v[92:95], v[166:169], v[210:213], v[92:95]
	v_mfma_f32_16x16x32_bf16 v[84:87], v[158:161], v[218:221], v[84:87]
	v_mfma_f32_16x16x32_bf16 v[76:79], v[166:169], v[218:221], v[76:79]
	v_mfma_f32_16x16x32_bf16 v[112:115], v[170:173], v[190:193], v[112:115]
	v_mfma_f32_16x16x32_bf16 v[104:107], v[178:181], v[190:193], v[104:107]
	v_mfma_f32_16x16x32_bf16 v[96:99], v[170:173], v[198:201], v[96:99]
	v_mfma_f32_16x16x32_bf16 v[88:91], v[178:181], v[198:201], v[88:91]
	v_mfma_f32_16x16x32_bf16 v[80:83], v[170:173], v[206:209], v[80:83]
	v_mfma_f32_16x16x32_bf16 v[72:75], v[178:181], v[206:209], v[72:75]
	v_mfma_f32_16x16x32_bf16 v[68:71], v[170:173], v[214:217], v[68:71]
	v_mfma_f32_16x16x32_bf16 v[64:67], v[178:181], v[214:217], v[64:67]
	v_mfma_f32_16x16x32_bf16 v[112:115], v[174:177], v[194:197], v[112:115]
	v_mfma_f32_16x16x32_bf16 v[104:107], v[182:185], v[194:197], v[104:107]
	v_mfma_f32_16x16x32_bf16 v[96:99], v[174:177], v[202:205], v[96:99]
	v_mfma_f32_16x16x32_bf16 v[88:91], v[182:185], v[202:205], v[88:91]
	v_mfma_f32_16x16x32_bf16 v[80:83], v[174:177], v[210:213], v[80:83]
	v_mfma_f32_16x16x32_bf16 v[72:75], v[182:185], v[210:213], v[72:75]
	v_mfma_f32_16x16x32_bf16 v[68:71], v[174:177], v[218:221], v[68:71]
	v_mfma_f32_16x16x32_bf16 v[64:67], v[182:185], v[218:221], v[64:67]
	s_barrier
	s_add_i32 s26, s74, s35
	v_lshl_add_u64 v[186:187], v[186:187], 0, s[8:9]
	s_mov_b32 m0, s26
	ds_read_b128 v[190:193], v150 offset:49152
	ds_read_b128 v[194:197], v150 offset:50176
	ds_read_b128 v[198:201], v150 offset:51200
	ds_read_b128 v[202:205], v150 offset:52224
	ds_read_b128 v[206:209], v150 offset:53248
	ds_read_b128 v[210:213], v150 offset:54272
	ds_read_b128 v[214:217], v150 offset:55296
	ds_read_b128 v[218:221], v150 offset:56320
	global_load_lds_dwordx4 v[186:187], off
	s_add_i32 m0, s26, 0x2000
	s_add_u32 s24, s24, 0x8080
	v_lshl_add_u64 v[186:187], v[222:223], 0, s[8:9]
	s_addc_u32 s25, s25, 0
	s_add_i32 s26, s75, s35
	global_load_lds_dwordx4 v[186:187], off
	v_lshl_add_u64 v[186:187], s[24:25], 0, v[132:133]
	s_mov_b32 m0, s26
	s_nop 0
	global_load_lds_dwordx4 v[186:187], off
	v_lshl_add_u64 v[186:187], s[24:25], 0, v[128:129]
	s_add_i32 m0, s26, 0x2000
	s_nop 0
	global_load_lds_dwordx4 v[186:187], off
	v_lshl_add_u64 v[186:187], v[224:225], 0, s[8:9]
	s_mov_b32 m0, s62
	s_nop 0
	global_load_lds_dwordx4 v[186:187], off
	v_lshl_add_u64 v[186:187], v[226:227], 0, s[8:9]
	s_mov_b32 m0, s63
	s_nop 0
	global_load_lds_dwordx4 v[186:187], off
	s_waitcnt vmcnt(8)
	s_waitcnt lgkmcnt(0)
	s_barrier
	s_waitcnt lgkmcnt(0)
	v_mfma_f32_16x16x32_bf16 v[60:63], v[154:157], v[190:193], v[60:63]
	v_mfma_f32_16x16x32_bf16 v[56:59], v[162:165], v[190:193], v[56:59]
	v_mfma_f32_16x16x32_bf16 v[52:55], v[154:157], v[198:201], v[52:55]
	v_mfma_f32_16x16x32_bf16 v[44:47], v[162:165], v[198:201], v[44:47]
	v_mfma_f32_16x16x32_bf16 v[36:39], v[154:157], v[206:209], v[36:39]
	v_mfma_f32_16x16x32_bf16 v[28:31], v[162:165], v[206:209], v[28:31]
	v_mfma_f32_16x16x32_bf16 v[20:23], v[154:157], v[214:217], v[20:23]
	v_mfma_f32_16x16x32_bf16 v[12:15], v[162:165], v[214:217], v[12:15]
	v_mfma_f32_16x16x32_bf16 v[60:63], v[158:161], v[194:197], v[60:63]
	v_mfma_f32_16x16x32_bf16 v[56:59], v[166:169], v[194:197], v[56:59]
	v_mfma_f32_16x16x32_bf16 v[52:55], v[158:161], v[202:205], v[52:55]
	v_mfma_f32_16x16x32_bf16 v[44:47], v[166:169], v[202:205], v[44:47]
	v_mfma_f32_16x16x32_bf16 v[36:39], v[158:161], v[210:213], v[36:39]
	v_mfma_f32_16x16x32_bf16 v[28:31], v[166:169], v[210:213], v[28:31]
	v_mfma_f32_16x16x32_bf16 v[20:23], v[158:161], v[218:221], v[20:23]
	v_mfma_f32_16x16x32_bf16 v[12:15], v[166:169], v[218:221], v[12:15]
	v_mfma_f32_16x16x32_bf16 v[48:51], v[170:173], v[190:193], v[48:51]
	v_mfma_f32_16x16x32_bf16 v[40:43], v[178:181], v[190:193], v[40:43]
	v_mfma_f32_16x16x32_bf16 v[32:35], v[170:173], v[198:201], v[32:35]
	v_mfma_f32_16x16x32_bf16 v[24:27], v[178:181], v[198:201], v[24:27]
	v_mfma_f32_16x16x32_bf16 v[16:19], v[170:173], v[206:209], v[16:19]
	v_mfma_f32_16x16x32_bf16 v[8:11], v[178:181], v[206:209], v[8:11]
	v_mfma_f32_16x16x32_bf16 v[4:7], v[170:173], v[214:217], v[4:7]
	v_mfma_f32_16x16x32_bf16 v[0:3], v[178:181], v[214:217], v[0:3]
	v_mfma_f32_16x16x32_bf16 v[48:51], v[174:177], v[194:197], v[48:51]
	v_mfma_f32_16x16x32_bf16 v[40:43], v[182:185], v[194:197], v[40:43]
	v_mfma_f32_16x16x32_bf16 v[32:35], v[174:177], v[202:205], v[32:35]
	v_mfma_f32_16x16x32_bf16 v[24:27], v[182:185], v[202:205], v[24:27]
	v_mfma_f32_16x16x32_bf16 v[16:19], v[174:177], v[210:213], v[16:19]
	v_mfma_f32_16x16x32_bf16 v[8:11], v[182:185], v[210:213], v[8:11]
	v_mfma_f32_16x16x32_bf16 v[4:7], v[174:177], v[218:221], v[4:7]
	v_mfma_f32_16x16x32_bf16 v[0:3], v[182:185], v[218:221], v[0:3]
	s_barrier
	s_add_i32 s86, s86, 2
	s_add_u32 s22, s22, 0x100
	s_addc_u32 s23, s23, 0
	s_add_u32 s97, s97, 0x100
	s_addc_u32 vcc_lo, vcc_lo, 0
	s_cmp_gt_u32 s86, 29
	s_cbranch_scc0 .LBB0_545
	s_and_b64 vcc, exec, s[10:11]
	s_cbranch_vccz .LBB0_548
	s_barrier

.Llr_done:
	s_waitcnt vmcnt(0)
	s_waitcnt vmcnt(0)
	s_setprio 0
	s_barrier
	s_and_saveexec_b64 s[2:3], s[28:29]
	s_cbranch_execz .LBB0_604
	s_add_i32 s4, 0, 0x24800
	v_mov_b32_e32 v0, s4
	s_waitcnt vmcnt(0) expcnt(0) lgkmcnt(0)
	ds_read_b32 v2, v0
	s_add_i32 s4, 0, 0x24804
	v_mov_b32_e32 v0, s4
	ds_read_b32 v0, v0
	s_waitcnt lgkmcnt(1)
	v_cmp_ne_u32_e32 vcc, 0, v2
	s_cbranch_vccnz .LBB0_568
	v_readlane_b32 s4, v253, 0
	s_mul_i32 s18, s69, s4
	s_add_u32 s4, s50, 0x1000
	s_addc_u32 s5, s51, 0
	s_add_u32 s6, s50, 0x1100
	s_addc_u32 s7, s51, 0
	s_add_u32 s8, s50, 0x1200
	s_addc_u32 s9, s51, 0
	s_add_u32 s10, s50, 0x1300
	s_mul_i32 s18, s18, s68
	s_addc_u32 s11, s51, 0
	s_mov_b32 s19, 1
	v_mov_b32_e32 v16, 0
	s_branch .LBB0_556

.LBB0_836:
	v_ashrrev_i32_e32 v1, 31, v8
	v_lshrrev_b32_e32 v1, 26, v1
	v_add_u32_e32 v1, v8, v1
	v_ashrrev_i32_e32 v9, 6, v1
	v_bfe_i32 v1, v8, 27, 1
	v_lshlrev_b32_e32 v0, 4, v8
	v_lshrrev_b32_e32 v1, 22, v1
	v_add_u32_e32 v1, v0, v1
	v_and_b32_e32 v1, 0xfffffc00, v1
	v_sub_u32_e32 v1, v0, v1
	v_lshrrev_b32_e32 v2, 4, v1
	v_bitop3_b32 v1, v2, v1, 32 bitop3:0x6c
	v_ashrrev_i32_e32 v3, 31, v1
	v_lshrrev_b32_e32 v3, 26, v3
	v_add_u32_e32 v3, v1, v3
	v_lshlrev_b32_e32 v2, 3, v9
	v_ashrrev_i32_e32 v11, 6, v3
	v_and_b32_e32 v3, 0xc0, v3
	v_and_b32_e32 v2, -16, v2
	v_sub_u32_e32 v1, v1, v3
	v_mov_b32_e32 v3, 1
	v_add_u32_e32 v2, v11, v2
	s_waitcnt vmcnt(0)
	v_lshlrev_b32_e32 v4, 5, v9
	v_ashrrev_i16_sdwa v1, v3, sext(v1) dst_sel:DWORD dst_unused:UNUSED_PAD src0_sel:DWORD src1_sel:BYTE_0
	v_and_b32_e32 v10, 32, v4
	v_bfe_i32 v12, v1, 0, 16
	v_lshlrev_b32_e32 v4, 1, v2
	v_lshlrev_b32_e32 v5, 2, v2
	v_lshrrev_b32_e32 v6, 2, v2
	v_and_b32_e32 v7, 3, v11
	s_movk_i32 s3, 0x3040
	s_add_i32 s0, s6, s0
	v_add_u32_e32 v1, v10, v12
	v_and_b32_e32 v4, 0x7ffc0, v4
	v_and_b32_e32 v6, 4, v6
	v_and_or_b32 v5, v5, 48, v7
	v_mul_lo_u32 v2, v2, s3
	s_ashr_i32 s1, s0, 31
	v_or3_b32 v4, v5, v4, v6
	v_add_lshl_u32 v128, v1, v2, 1
	v_lshlrev_b32_e32 v1, 1, v1
	v_add_u32_e32 v0, 0x2000, v0
	s_lshr_b32 s1, s1, 26
	v_lshl_add_u32 v130, v4, 13, v1
	v_ashrrev_i32_e32 v1, 31, v0
	s_add_i32 s1, s0, s1
	v_lshrrev_b32_e32 v1, 22, v1
	s_ashr_i32 s6, s1, 6
	s_and_b32 s1, s1, 0xffc0
	v_add_u32_e32 v1, v0, v1
	s_sub_i32 s1, s0, s1
	v_ashrrev_i32_e32 v13, 10, v1
	s_bfe_i32 s0, s1, 0x80000
	v_mul_i32_i24_e32 v1, 0x400, v13
	s_bfe_u32 s0, s0, 0x3000c
	v_sub_u32_e32 v0, v0, v1
	s_add_i32 s7, s1, s0
	v_lshrrev_b32_e32 v1, 4, v0
	s_bfe_i32 s0, s7, 0x80000
	s_and_b32 s7, s7, 0xf8
	v_bitop3_b32 v0, v1, v0, 32 bitop3:0x6c
	s_sub_i32 s1, s1, s7
	v_ashrrev_i32_e32 v2, 31, v0
	s_lshl_b32 s6, s6, 3
	s_sext_i32_i8 s1, s1
	v_lshrrev_b32_e32 v2, 26, v2
	s_sext_i32_i16 s0, s0
	s_add_i32 s72, s6, s1
	v_add_u32_e32 v2, v0, v2
	s_lshr_b32 s0, s0, 3
	s_mul_hi_i32 s1, s72, 0x608000
	s_ashr_i32 s4, s2, 6
	v_lshlrev_b32_e32 v1, 3, v13
	v_ashrrev_i32_e32 v14, 6, v2
	v_and_b32_e32 v2, 0xc0, v2
	s_bfe_i64 s[6:7], s[0:1], 0x100000
	v_and_b32_e32 v1, -16, v1
	v_sub_u32_e32 v0, v0, v2
	s_ashr_i32 s5, s2, 8
	s_lshl_b32 s24, s4, 10
	s_lshl_b64 s[6:7], s[6:7], 21
	v_add_u32_e32 v1, v14, v1
	v_lshlrev_b32_e32 v4, 5, v13
	v_ashrrev_i16_sdwa v0, v3, sext(v0) dst_sel:DWORD dst_unused:UNUSED_PAD src0_sel:DWORD src1_sel:BYTE_0
	s_add_u32 s20, s70, s6
	v_and_b32_e32 v15, 32, v4
	v_bfe_i32 v16, v0, 0, 16
	v_lshlrev_b32_e32 v2, 1, v1
	v_lshlrev_b32_e32 v3, 2, v1
	v_lshrrev_b32_e32 v4, 2, v1
	v_and_b32_e32 v5, 3, v14
	s_addc_u32 s21, s71, s7
	s_add_i32 s25, s24, 0
	v_add_u32_e32 v0, v15, v16
	v_and_b32_e32 v2, 0x7ffc0, v2
	v_and_b32_e32 v4, 4, v4
	v_and_or_b32 v3, v3, 48, v5
	v_mul_lo_u32 v1, v1, s3
	s_add_i32 m0, s25, 0x10000
	v_or3_b32 v2, v3, v2, v4
	v_add_lshl_u32 v132, v0, v1, 1
	v_lshlrev_b32_e32 v0, 1, v0
	global_load_lds_dwordx4 v130, s[20:21]
	s_add_i32 m0, s25, 0x12000
	v_lshl_add_u32 v134, v2, 13, v0
	s_add_u32 s6, s20, 0x10000
	global_load_lds_dwordx4 v134, s[20:21]
	s_addc_u32 s7, s21, 0
	s_add_i32 m0, s25, 0x14000
	s_mul_i32 s8, s72, 0x608000
	global_load_lds_dwordx4 v130, s[6:7]
	s_add_i32 m0, s25, 0x16000
	s_add_u32 s18, s76, s8
	s_addc_u32 s19, s77, s1
	s_add_i32 s26, s25, 0x2000
	global_load_lds_dwordx4 v134, s[6:7]
	s_mov_b32 m0, s25
	s_add_u32 s6, s18, 0x304000
	global_load_lds_dwordx4 v128, s[18:19]
	s_mov_b32 m0, s26
	s_addc_u32 s7, s19, 0
	s_add_i32 s27, s25, 0x4000
	global_load_lds_dwordx4 v132, s[18:19]
	s_mov_b32 m0, s27
	s_add_i32 s35, s25, 0x6000
	global_load_lds_dwordx4 v128, s[6:7]
	s_mov_b32 m0, s35
	v_mov_b32_e32 v137, 0
	global_load_lds_dwordx4 v132, s[6:7]
	v_mov_b32_e32 v131, v137
	v_mov_b32_e32 v135, v137
	v_mov_b32_e32 v129, v137
	v_mov_b32_e32 v133, v137
	s_cmp_eq_u32 s5, 1
	s_mov_b32 s1, 0
	v_lshl_add_u64 v[6:7], s[20:21], 0, v[130:131]
	v_lshl_add_u64 v[4:5], s[20:21], 0, v[134:135]
	v_lshl_add_u64 v[0:1], s[18:19], 0, v[128:129]
	s_cselect_b64 s[6:7], -1, 0
	s_cmp_lg_u32 s5, 1
	v_lshl_add_u64 v[2:3], s[18:19], 0, v[132:133]
	s_cbranch_scc1 .LBB0_838
	s_barrier
	s_setprio 1

.LBB0_850:
	ds_read_b128 v[154:157], v149
	ds_read_b128 v[158:161], v149 offset:1024
	ds_read_b128 v[162:165], v149 offset:2048
	ds_read_b128 v[166:169], v149 offset:3072
	ds_read_b128 v[170:173], v150
	ds_read_b128 v[174:177], v150 offset:1024
	ds_read_b128 v[178:181], v150 offset:2048
	ds_read_b128 v[182:185], v150 offset:3072
	s_add_u32 s4, s18, 0x100
	s_addc_u32 s5, s19, 0
	s_cmp_eq_u32 s79, 60
	s_cselect_b32 s23, s15, s5
	s_cselect_b32 s22, s14, s4
	s_cselect_b32 s21, s13, s78
	s_cselect_b32 s20, s74, s75
	v_lshl_add_u64 v[186:187], s[18:19], 0, v[138:139]
	s_add_i32 m0, s25, 0xc000
	ds_read_b128 v[190:193], v151
	ds_read_b128 v[194:197], v151 offset:1024
	ds_read_b128 v[198:201], v151 offset:2048
	ds_read_b128 v[202:205], v151 offset:3072
	ds_read_b128 v[206:209], v151 offset:4096
	ds_read_b128 v[210:213], v151 offset:5120
	ds_read_b128 v[214:217], v151 offset:6144
	ds_read_b128 v[218:221], v151 offset:7168
	global_load_lds_dwordx4 v[186:187], off
	v_lshl_add_u64 v[186:187], s[18:19], 0, v[140:141]
	s_add_i32 m0, s25, 0xe000
	s_nop 0
	global_load_lds_dwordx4 v[186:187], off
	s_waitcnt vmcnt(8)
	s_waitcnt lgkmcnt(0)
	s_barrier
	s_waitcnt lgkmcnt(0)
	v_mfma_f32_16x16x32_bf16 v[124:127], v[154:157], v[190:193], v[124:127]
	v_mfma_f32_16x16x32_bf16 v[120:123], v[162:165], v[190:193], v[120:123]
	v_mfma_f32_16x16x32_bf16 v[116:119], v[154:157], v[198:201], v[116:119]
	v_mfma_f32_16x16x32_bf16 v[108:111], v[162:165], v[198:201], v[108:111]
	v_mfma_f32_16x16x32_bf16 v[100:103], v[154:157], v[206:209], v[100:103]
	v_mfma_f32_16x16x32_bf16 v[92:95], v[162:165], v[206:209], v[92:95]
	v_mfma_f32_16x16x32_bf16 v[84:87], v[154:157], v[214:217], v[84:87]
	v_mfma_f32_16x16x32_bf16 v[76:79], v[162:165], v[214:217], v[76:79]
	v_mfma_f32_16x16x32_bf16 v[124:127], v[158:161], v[194:197], v[124:127]
	v_mfma_f32_16x16x32_bf16 v[120:123], v[166:169], v[194:197], v[120:123]
	v_mfma_f32_16x16x32_bf16 v[116:119], v[158:161], v[202:205], v[116:119]
	v_mfma_f32_16x16x32_bf16 v[108:111], v[166:169], v[202:205], v[108:111]
	v_mfma_f32_16x16x32_bf16 v[100:103], v[158:161], v[210:213], v[100:103]
	v_mfma_f32_16x16x32_bf16 v[92:95], v[166:169], v[210:213], v[92:95]
	v_mfma_f32_16x16x32_bf16 v[84:87], v[158:161], v[218:221], v[84:87]
	v_mfma_f32_16x16x32_bf16 v[76:79], v[166:169], v[218:221], v[76:79]
	v_mfma_f32_16x16x32_bf16 v[112:115], v[170:173], v[190:193], v[112:115]
	v_mfma_f32_16x16x32_bf16 v[104:107], v[178:181], v[190:193], v[104:107]
	v_mfma_f32_16x16x32_bf16 v[96:99], v[170:173], v[198:201], v[96:99]
	v_mfma_f32_16x16x32_bf16 v[88:91], v[178:181], v[198:201], v[88:91]
	v_mfma_f32_16x16x32_bf16 v[80:83], v[170:173], v[206:209], v[80:83]
	v_mfma_f32_16x16x32_bf16 v[72:75], v[178:181], v[206:209], v[72:75]
	v_mfma_f32_16x16x32_bf16 v[68:71], v[170:173], v[214:217], v[68:71]
	v_mfma_f32_16x16x32_bf16 v[64:67], v[178:181], v[214:217], v[64:67]
	v_mfma_f32_16x16x32_bf16 v[112:115], v[174:177], v[194:197], v[112:115]
	v_mfma_f32_16x16x32_bf16 v[104:107], v[182:185], v[194:197], v[104:107]
	v_mfma_f32_16x16x32_bf16 v[96:99], v[174:177], v[202:205], v[96:99]
	v_mfma_f32_16x16x32_bf16 v[88:91], v[182:185], v[202:205], v[88:91]
	v_mfma_f32_16x16x32_bf16 v[80:83], v[174:177], v[210:213], v[80:83]
	v_mfma_f32_16x16x32_bf16 v[72:75], v[182:185], v[210:213], v[72:75]
	v_mfma_f32_16x16x32_bf16 v[68:71], v[174:177], v[218:221], v[68:71]
	v_mfma_f32_16x16x32_bf16 v[64:67], v[182:185], v[218:221], v[64:67]
	s_barrier
	s_add_i32 s18, s38, s24
	v_lshl_add_u64 v[186:187], s[20:21], 0, v[130:131]
	s_mov_b32 m0, s18
	ds_read_b128 v[190:193], v151 offset:16384
	ds_read_b128 v[194:197], v151 offset:17408
	ds_read_b128 v[198:201], v151 offset:18432
	ds_read_b128 v[202:205], v151 offset:19456
	ds_read_b128 v[206:209], v151 offset:20480
	ds_read_b128 v[210:213], v151 offset:21504
	ds_read_b128 v[214:217], v151 offset:22528
	ds_read_b128 v[218:221], v151 offset:23552
	global_load_lds_dwordx4 v[186:187], off
	s_add_i32 m0, s18, 0x2000
	s_add_u32 s18, s20, 0x10000
	v_lshl_add_u64 v[222:223], s[20:21], 0, v[134:135]
	s_addc_u32 s19, s21, 0
	s_add_i32 s80, s39, s24
	global_load_lds_dwordx4 v[222:223], off
	v_lshl_add_u64 v[224:225], s[18:19], 0, v[130:131]
	s_mov_b32 m0, s80
	v_lshl_add_u64 v[226:227], s[22:23], 0, v[132:133]
	global_load_lds_dwordx4 v[224:225], off
	v_lshl_add_u64 v[224:225], s[18:19], 0, v[134:135]
	s_add_i32 m0, s80, 0x2000
	s_nop 0
	global_load_lds_dwordx4 v[224:225], off
	v_lshl_add_u64 v[224:225], s[22:23], 0, v[128:129]
	s_mov_b32 m0, s25
	s_nop 0
	global_load_lds_dwordx4 v[224:225], off
	s_mov_b32 m0, s26
	s_nop 0
	global_load_lds_dwordx4 v[226:227], off
	s_waitcnt vmcnt(8)
	s_waitcnt lgkmcnt(0)
	s_barrier
	s_waitcnt lgkmcnt(0)
	v_mfma_f32_16x16x32_bf16 v[60:63], v[154:157], v[190:193], v[60:63]
	v_mfma_f32_16x16x32_bf16 v[56:59], v[162:165], v[190:193], v[56:59]
	v_mfma_f32_16x16x32_bf16 v[52:55], v[154:157], v[198:201], v[52:55]
	v_mfma_f32_16x16x32_bf16 v[44:47], v[162:165], v[198:201], v[44:47]
	v_mfma_f32_16x16x32_bf16 v[36:39], v[154:157], v[206:209], v[36:39]
	v_mfma_f32_16x16x32_bf16 v[28:31], v[162:165], v[206:209], v[28:31]
	v_mfma_f32_16x16x32_bf16 v[20:23], v[154:157], v[214:217], v[20:23]
	v_mfma_f32_16x16x32_bf16 v[12:15], v[162:165], v[214:217], v[12:15]
	v_mfma_f32_16x16x32_bf16 v[60:63], v[158:161], v[194:197], v[60:63]
	v_mfma_f32_16x16x32_bf16 v[56:59], v[166:169], v[194:197], v[56:59]
	v_mfma_f32_16x16x32_bf16 v[52:55], v[158:161], v[202:205], v[52:55]
	v_mfma_f32_16x16x32_bf16 v[44:47], v[166:169], v[202:205], v[44:47]
	v_mfma_f32_16x16x32_bf16 v[36:39], v[158:161], v[210:213], v[36:39]
	v_mfma_f32_16x16x32_bf16 v[28:31], v[166:169], v[210:213], v[28:31]
	v_mfma_f32_16x16x32_bf16 v[20:23], v[158:161], v[218:221], v[20:23]
	v_mfma_f32_16x16x32_bf16 v[12:15], v[166:169], v[218:221], v[12:15]
	v_mfma_f32_16x16x32_bf16 v[48:51], v[170:173], v[190:193], v[48:51]
	v_mfma_f32_16x16x32_bf16 v[40:43], v[178:181], v[190:193], v[40:43]
	v_mfma_f32_16x16x32_bf16 v[32:35], v[170:173], v[198:201], v[32:35]
	v_mfma_f32_16x16x32_bf16 v[24:27], v[178:181], v[198:201], v[24:27]
	v_mfma_f32_16x16x32_bf16 v[16:19], v[170:173], v[206:209], v[16:19]
	v_mfma_f32_16x16x32_bf16 v[8:11], v[178:181], v[206:209], v[8:11]
	v_mfma_f32_16x16x32_bf16 v[4:7], v[170:173], v[214:217], v[4:7]
	v_mfma_f32_16x16x32_bf16 v[0:3], v[178:181], v[214:217], v[0:3]
	v_mfma_f32_16x16x32_bf16 v[48:51], v[174:177], v[194:197], v[48:51]
	v_mfma_f32_16x16x32_bf16 v[40:43], v[182:185], v[194:197], v[40:43]
	v_mfma_f32_16x16x32_bf16 v[32:35], v[174:177], v[202:205], v[32:35]
	v_mfma_f32_16x16x32_bf16 v[24:27], v[182:185], v[202:205], v[24:27]
	v_mfma_f32_16x16x32_bf16 v[16:19], v[174:177], v[210:213], v[16:19]
	v_mfma_f32_16x16x32_bf16 v[8:11], v[182:185], v[210:213], v[8:11]
	v_mfma_f32_16x16x32_bf16 v[4:7], v[174:177], v[218:221], v[4:7]
	v_mfma_f32_16x16x32_bf16 v[0:3], v[182:185], v[218:221], v[0:3]
	s_barrier
	s_add_i32 s80, 0, 0x18000
	s_add_i32 s81, 0, 0x1c000
	v_add_u32_e32 v166, s80, v147
	v_add_u32_e32 v182, s81, v147
	ds_read_b128 v[154:157], v166
	ds_read_b128 v[158:161], v166 offset:1024
	ds_read_b128 v[162:165], v166 offset:2048
	ds_read_b128 v[166:169], v166 offset:3072
	ds_read_b128 v[170:173], v182
	ds_read_b128 v[174:177], v182 offset:1024
	ds_read_b128 v[178:181], v182 offset:2048
	ds_read_b128 v[182:185], v182 offset:3072
	s_add_u32 s18, s22, 0x304000
	s_addc_u32 s19, s23, 0
	s_mov_b32 m0, s27
	v_lshl_add_u64 v[228:229], s[18:19], 0, v[128:129]
	ds_read_b128 v[190:193], v151 offset:32768
	ds_read_b128 v[194:197], v151 offset:33792
	ds_read_b128 v[198:201], v151 offset:34816
	ds_read_b128 v[202:205], v151 offset:35840
	ds_read_b128 v[206:209], v151 offset:36864
	ds_read_b128 v[210:213], v151 offset:37888
	ds_read_b128 v[214:217], v151 offset:38912
	ds_read_b128 v[218:221], v151 offset:39936
	global_load_lds_dwordx4 v[228:229], off
	v_lshl_add_u64 v[228:229], s[18:19], 0, v[132:133]
	s_mov_b32 m0, s35
	s_nop 0
	global_load_lds_dwordx4 v[228:229], off
	s_waitcnt vmcnt(8)
	s_waitcnt lgkmcnt(0)
	s_barrier
	s_waitcnt lgkmcnt(0)
	v_mfma_f32_16x16x32_bf16 v[124:127], v[154:157], v[190:193], v[124:127]
	v_mfma_f32_16x16x32_bf16 v[120:123], v[162:165], v[190:193], v[120:123]
	v_mfma_f32_16x16x32_bf16 v[116:119], v[154:157], v[198:201], v[116:119]
	v_mfma_f32_16x16x32_bf16 v[108:111], v[162:165], v[198:201], v[108:111]
	v_mfma_f32_16x16x32_bf16 v[100:103], v[154:157], v[206:209], v[100:103]
	v_mfma_f32_16x16x32_bf16 v[92:95], v[162:165], v[206:209], v[92:95]
	v_mfma_f32_16x16x32_bf16 v[84:87], v[154:157], v[214:217], v[84:87]
	v_mfma_f32_16x16x32_bf16 v[76:79], v[162:165], v[214:217], v[76:79]
	v_mfma_f32_16x16x32_bf16 v[124:127], v[158:161], v[194:197], v[124:127]
	v_mfma_f32_16x16x32_bf16 v[120:123], v[166:169], v[194:197], v[120:123]
	v_mfma_f32_16x16x32_bf16 v[116:119], v[158:161], v[202:205], v[116:119]
	v_mfma_f32_16x16x32_bf16 v[108:111], v[166:169], v[202:205], v[108:111]
	v_mfma_f32_16x16x32_bf16 v[100:103], v[158:161], v[210:213], v[100:103]
	v_mfma_f32_16x16x32_bf16 v[92:95], v[166:169], v[210:213], v[92:95]
	v_mfma_f32_16x16x32_bf16 v[84:87], v[158:161], v[218:221], v[84:87]
	v_mfma_f32_16x16x32_bf16 v[76:79], v[166:169], v[218:221], v[76:79]
	v_mfma_f32_16x16x32_bf16 v[112:115], v[170:173], v[190:193], v[112:115]
	v_mfma_f32_16x16x32_bf16 v[104:107], v[178:181], v[190:193], v[104:107]
	v_mfma_f32_16x16x32_bf16 v[96:99], v[170:173], v[198:201], v[96:99]
	v_mfma_f32_16x16x32_bf16 v[88:91], v[178:181], v[198:201], v[88:91]
	v_mfma_f32_16x16x32_bf16 v[80:83], v[170:173], v[206:209], v[80:83]
	v_mfma_f32_16x16x32_bf16 v[72:75], v[178:181], v[206:209], v[72:75]
	v_mfma_f32_16x16x32_bf16 v[68:71], v[170:173], v[214:217], v[68:71]
	v_mfma_f32_16x16x32_bf16 v[64:67], v[178:181], v[214:217], v[64:67]
	v_mfma_f32_16x16x32_bf16 v[112:115], v[174:177], v[194:197], v[112:115]
	v_mfma_f32_16x16x32_bf16 v[104:107], v[182:185], v[194:197], v[104:107]
	v_mfma_f32_16x16x32_bf16 v[96:99], v[174:177], v[202:205], v[96:99]
	v_mfma_f32_16x16x32_bf16 v[88:91], v[182:185], v[202:205], v[88:91]
	v_mfma_f32_16x16x32_bf16 v[80:83], v[174:177], v[210:213], v[80:83]
	v_mfma_f32_16x16x32_bf16 v[72:75], v[182:185], v[210:213], v[72:75]
	v_mfma_f32_16x16x32_bf16 v[68:71], v[174:177], v[218:221], v[68:71]
	v_mfma_f32_16x16x32_bf16 v[64:67], v[182:185], v[218:221], v[64:67]
	s_barrier
	s_add_i32 s18, s80, s24
	v_lshl_add_u64 v[186:187], v[186:187], 0, s[8:9]
	s_mov_b32 m0, s18
	ds_read_b128 v[190:193], v151 offset:49152
	ds_read_b128 v[194:197], v151 offset:50176
	ds_read_b128 v[198:201], v151 offset:51200
	ds_read_b128 v[202:205], v151 offset:52224
	ds_read_b128 v[206:209], v151 offset:53248
	ds_read_b128 v[210:213], v151 offset:54272
	ds_read_b128 v[214:217], v151 offset:55296
	ds_read_b128 v[218:221], v151 offset:56320
	global_load_lds_dwordx4 v[186:187], off
	s_add_i32 m0, s18, 0x2000
	s_add_u32 s18, s20, 0x10080
	v_lshl_add_u64 v[186:187], v[222:223], 0, s[8:9]
	s_addc_u32 s19, s21, 0
	s_add_i32 s20, s81, s24
	global_load_lds_dwordx4 v[186:187], off
	v_lshl_add_u64 v[186:187], s[18:19], 0, v[130:131]
	s_mov_b32 m0, s20
	s_nop 0
	global_load_lds_dwordx4 v[186:187], off
	v_lshl_add_u64 v[186:187], s[18:19], 0, v[134:135]
	s_add_i32 m0, s20, 0x2000
	s_nop 0
	global_load_lds_dwordx4 v[186:187], off
	v_lshl_add_u64 v[186:187], v[224:225], 0, s[8:9]
	s_mov_b32 m0, s36
	s_nop 0
	global_load_lds_dwordx4 v[186:187], off
	v_lshl_add_u64 v[186:187], v[226:227], 0, s[8:9]
	s_mov_b32 m0, s37
	s_nop 0
	global_load_lds_dwordx4 v[186:187], off
	s_waitcnt vmcnt(8)
	s_waitcnt lgkmcnt(0)
	s_barrier
	s_waitcnt lgkmcnt(0)
	v_mfma_f32_16x16x32_bf16 v[60:63], v[154:157], v[190:193], v[60:63]
	v_mfma_f32_16x16x32_bf16 v[56:59], v[162:165], v[190:193], v[56:59]
	v_mfma_f32_16x16x32_bf16 v[52:55], v[154:157], v[198:201], v[52:55]
	v_mfma_f32_16x16x32_bf16 v[44:47], v[162:165], v[198:201], v[44:47]
	v_mfma_f32_16x16x32_bf16 v[36:39], v[154:157], v[206:209], v[36:39]
	v_mfma_f32_16x16x32_bf16 v[28:31], v[162:165], v[206:209], v[28:31]
	v_mfma_f32_16x16x32_bf16 v[20:23], v[154:157], v[214:217], v[20:23]
	v_mfma_f32_16x16x32_bf16 v[12:15], v[162:165], v[214:217], v[12:15]
	v_mfma_f32_16x16x32_bf16 v[60:63], v[158:161], v[194:197], v[60:63]
	v_mfma_f32_16x16x32_bf16 v[56:59], v[166:169], v[194:197], v[56:59]
	v_mfma_f32_16x16x32_bf16 v[52:55], v[158:161], v[202:205], v[52:55]
	v_mfma_f32_16x16x32_bf16 v[44:47], v[166:169], v[202:205], v[44:47]
	v_mfma_f32_16x16x32_bf16 v[36:39], v[158:161], v[210:213], v[36:39]
	v_mfma_f32_16x16x32_bf16 v[28:31], v[166:169], v[210:213], v[28:31]
	v_mfma_f32_16x16x32_bf16 v[20:23], v[158:161], v[218:221], v[20:23]
	v_mfma_f32_16x16x32_bf16 v[12:15], v[166:169], v[218:221], v[12:15]
	v_mfma_f32_16x16x32_bf16 v[48:51], v[170:173], v[190:193], v[48:51]
	v_mfma_f32_16x16x32_bf16 v[40:43], v[178:181], v[190:193], v[40:43]
	v_mfma_f32_16x16x32_bf16 v[32:35], v[170:173], v[198:201], v[32:35]
	v_mfma_f32_16x16x32_bf16 v[24:27], v[178:181], v[198:201], v[24:27]
	v_mfma_f32_16x16x32_bf16 v[16:19], v[170:173], v[206:209], v[16:19]
	v_mfma_f32_16x16x32_bf16 v[8:11], v[178:181], v[206:209], v[8:11]
	v_mfma_f32_16x16x32_bf16 v[4:7], v[170:173], v[214:217], v[4:7]
	v_mfma_f32_16x16x32_bf16 v[0:3], v[178:181], v[214:217], v[0:3]
	v_mfma_f32_16x16x32_bf16 v[48:51], v[174:177], v[194:197], v[48:51]
	v_mfma_f32_16x16x32_bf16 v[40:43], v[182:185], v[194:197], v[40:43]
	v_mfma_f32_16x16x32_bf16 v[32:35], v[174:177], v[202:205], v[32:35]
	v_mfma_f32_16x16x32_bf16 v[24:27], v[182:185], v[202:205], v[24:27]
	v_mfma_f32_16x16x32_bf16 v[16:19], v[174:177], v[210:213], v[16:19]
	v_mfma_f32_16x16x32_bf16 v[8:11], v[182:185], v[210:213], v[8:11]
	v_mfma_f32_16x16x32_bf16 v[4:7], v[174:177], v[218:221], v[4:7]
	v_mfma_f32_16x16x32_bf16 v[0:3], v[182:185], v[218:221], v[0:3]
	s_barrier
	s_add_i32 s79, s79, 2
	s_add_u32 s75, s75, 0x100
	s_addc_u32 s78, s78, 0
	s_cmp_gt_u32 s79, 61
	s_mov_b64 s[18:19], s[4:5]
	s_cbranch_scc0 .LBB0_850
	s_and_b64 vcc, exec, s[10:11]
	s_cbranch_vccz .LBB0_853
	s_barrier

.LBB0_881:
	v_ashrrev_i32_e32 v1, 31, v8
	v_lshrrev_b32_e32 v1, 26, v1
	v_add_u32_e32 v1, v8, v1
	v_ashrrev_i32_e32 v9, 6, v1
	v_bfe_i32 v1, v8, 27, 1
	v_lshlrev_b32_e32 v0, 4, v8
	v_lshrrev_b32_e32 v1, 22, v1
	v_add_u32_e32 v1, v0, v1
	v_and_b32_e32 v1, 0xfffffc00, v1
	v_sub_u32_e32 v1, v0, v1
	v_lshrrev_b32_e32 v2, 4, v1
	v_bitop3_b32 v1, v2, v1, 32 bitop3:0x6c
	v_ashrrev_i32_e32 v3, 31, v1
	v_lshrrev_b32_e32 v3, 26, v3
	v_add_u32_e32 v3, v1, v3
	v_lshlrev_b32_e32 v2, 3, v9
	v_ashrrev_i32_e32 v11, 6, v3
	v_and_b32_e32 v3, 0xc0, v3
	v_and_b32_e32 v2, -16, v2
	v_sub_u32_e32 v1, v1, v3
	v_mov_b32_e32 v3, 1
	s_ashr_i32 s0, s3, 3
	v_add_u32_e32 v2, v11, v2
	v_lshlrev_b32_e32 v4, 5, v9
	v_ashrrev_i16_sdwa v1, v3, sext(v1) dst_sel:DWORD dst_unused:UNUSED_PAD src0_sel:DWORD src1_sel:BYTE_0
	v_and_b32_e32 v10, 32, v4
	v_bfe_i32 v12, v1, 0, 16
	v_lshlrev_b32_e32 v4, 1, v2
	v_lshlrev_b32_e32 v5, 2, v2
	v_lshrrev_b32_e32 v6, 2, v2
	v_and_b32_e32 v7, 3, v11
	s_movk_i32 s3, 0x3040
	s_add_i32 s0, s6, s0
	v_add_u32_e32 v1, v10, v12
	v_and_b32_e32 v4, 0x7ffc0, v4
	v_and_b32_e32 v6, 4, v6
	v_and_or_b32 v5, v5, 48, v7
	v_mul_lo_u32 v2, v2, s3
	s_ashr_i32 s1, s0, 31
	v_or3_b32 v4, v5, v4, v6
	v_add_lshl_u32 v128, v1, v2, 1
	v_lshlrev_b32_e32 v1, 1, v1
	v_add_u32_e32 v0, 0x2000, v0
	s_lshr_b32 s1, s1, 26
	v_lshl_add_u32 v130, v4, 13, v1
	v_ashrrev_i32_e32 v1, 31, v0
	s_add_i32 s1, s0, s1
	v_lshrrev_b32_e32 v1, 22, v1
	s_ashr_i32 s6, s1, 6
	s_andn2_b32 s1, s1, 63
	v_add_u32_e32 v1, v0, v1
	s_sub_i32 s1, s0, s1
	v_ashrrev_i32_e32 v13, 10, v1
	s_bfe_i32 s0, s1, 0x80000
	v_mul_i32_i24_e32 v1, 0x400, v13
	s_bfe_u32 s0, s0, 0x3000c
	v_sub_u32_e32 v0, v0, v1
	s_add_i32 s7, s1, s0
	v_lshrrev_b32_e32 v1, 4, v0
	s_bfe_i32 s0, s7, 0x80000
	s_and_b32 s7, s7, 0xf8
	v_bitop3_b32 v0, v1, v0, 32 bitop3:0x6c
	s_sub_i32 s1, s1, s7
	v_ashrrev_i32_e32 v2, 31, v0
	s_lshl_b32 s6, s6, 3
	s_sext_i32_i8 s1, s1
	v_lshrrev_b32_e32 v2, 26, v2
	s_sext_i32_i16 s0, s0
	s_add_i32 s13, s6, s1
	v_add_u32_e32 v2, v0, v2
	s_lshr_b32 s0, s0, 3
	s_mul_hi_i32 s1, s13, 0x608000
	s_ashr_i32 s4, s2, 6
	v_lshlrev_b32_e32 v1, 3, v13
	v_ashrrev_i32_e32 v14, 6, v2
	v_and_b32_e32 v2, 0xc0, v2
	s_bfe_i64 s[6:7], s[0:1], 0x100000
	v_and_b32_e32 v1, -16, v1
	v_sub_u32_e32 v0, v0, v2
	s_ashr_i32 s5, s2, 8
	s_lshl_b32 s24, s4, 10
	s_lshl_b64 s[6:7], s[6:7], 21
	v_add_u32_e32 v1, v14, v1
	v_lshlrev_b32_e32 v4, 5, v13
	v_ashrrev_i16_sdwa v0, v3, sext(v0) dst_sel:DWORD dst_unused:UNUSED_PAD src0_sel:DWORD src1_sel:BYTE_0
	s_add_u32 s22, s70, s6
	v_and_b32_e32 v15, 32, v4
	v_bfe_i32 v16, v0, 0, 16
	v_lshlrev_b32_e32 v2, 1, v1
	v_lshlrev_b32_e32 v3, 2, v1
	v_lshrrev_b32_e32 v4, 2, v1
	v_and_b32_e32 v5, 3, v14
	s_addc_u32 s23, s71, s7
	s_add_i32 s25, s24, 0
	v_add_u32_e32 v0, v15, v16
	v_and_b32_e32 v2, 0x7ffc0, v2
	v_and_b32_e32 v4, 4, v4
	v_and_or_b32 v3, v3, 48, v5
	v_mul_lo_u32 v1, v1, s3
	s_add_i32 m0, s25, 0x10000
	v_or3_b32 v2, v3, v2, v4
	v_add_lshl_u32 v132, v0, v1, 1
	v_lshlrev_b32_e32 v0, 1, v0
	global_load_lds_dwordx4 v130, s[22:23]
	s_add_i32 m0, s25, 0x12000
	v_lshl_add_u32 v134, v2, 13, v0
	s_add_u32 s6, s22, 0x10000
	global_load_lds_dwordx4 v134, s[22:23]
	s_addc_u32 s7, s23, 0
	s_add_i32 m0, s25, 0x14000
	s_mul_i32 s8, s13, 0x608000
	global_load_lds_dwordx4 v130, s[6:7]
	s_add_i32 m0, s25, 0x16000
	s_add_u32 s20, s76, s8
	s_addc_u32 s21, s77, s1
	s_add_i32 s26, s25, 0x2000
	global_load_lds_dwordx4 v134, s[6:7]
	s_mov_b32 m0, s25
	s_add_u32 s6, s20, 0x304000
	global_load_lds_dwordx4 v128, s[20:21]
	s_mov_b32 m0, s26
	s_addc_u32 s7, s21, 0
	s_add_i32 s27, s25, 0x4000
	global_load_lds_dwordx4 v132, s[20:21]
	s_mov_b32 m0, s27
	s_add_i32 s35, s25, 0x6000
	global_load_lds_dwordx4 v128, s[6:7]
	s_mov_b32 m0, s35
	v_mov_b32_e32 v137, 0
	global_load_lds_dwordx4 v132, s[6:7]
	v_mov_b32_e32 v131, v137
	v_mov_b32_e32 v135, v137
	v_mov_b32_e32 v129, v137
	v_mov_b32_e32 v133, v137
	s_cmp_eq_u32 s5, 1
	s_mov_b32 s1, 0
	v_lshl_add_u64 v[6:7], s[22:23], 0, v[130:131]
	v_lshl_add_u64 v[4:5], s[22:23], 0, v[134:135]
	v_lshl_add_u64 v[0:1], s[20:21], 0, v[128:129]
	s_cselect_b64 s[6:7], -1, 0
	s_cmp_lg_u32 s5, 1
	v_lshl_add_u64 v[2:3], s[20:21], 0, v[132:133]
	s_cbranch_scc1 .LBB0_883
	s_barrier
	s_setprio 1

.LBB0_896:
	ds_read_b128 v[154:157], v149
	ds_read_b128 v[158:161], v149 offset:1024
	ds_read_b128 v[162:165], v149 offset:2048
	ds_read_b128 v[166:169], v149 offset:3072
	ds_read_b128 v[170:173], v150
	ds_read_b128 v[174:177], v150 offset:1024
	ds_read_b128 v[178:181], v150 offset:2048
	ds_read_b128 v[182:185], v150 offset:3072
	s_mov_b64 s[78:79], s[20:21]
	s_add_u32 s20, s78, 0x100
	s_addc_u32 s21, s79, 0
	s_cmp_eq_u32 s74, 0
	s_cselect_b32 s23, s17, s21
	s_cselect_b32 s22, s16, s20
	s_cselect_b32 s5, s15, s72
	s_cselect_b32 s4, s66, s67
	v_lshl_add_u64 v[186:187], s[78:79], 0, v[138:139]
	s_add_i32 m0, s25, 0xc000
	ds_read_b128 v[190:193], v151
	ds_read_b128 v[194:197], v151 offset:1024
	ds_read_b128 v[198:201], v151 offset:2048
	ds_read_b128 v[202:205], v151 offset:3072
	ds_read_b128 v[206:209], v151 offset:4096
	ds_read_b128 v[210:213], v151 offset:5120
	ds_read_b128 v[214:217], v151 offset:6144
	ds_read_b128 v[218:221], v151 offset:7168
	global_load_lds_dwordx4 v[186:187], off
	v_lshl_add_u64 v[186:187], s[78:79], 0, v[140:141]
	s_add_i32 m0, s25, 0xe000
	s_nop 0
	global_load_lds_dwordx4 v[186:187], off
	s_waitcnt vmcnt(8)
	s_waitcnt lgkmcnt(0)
	s_barrier
	s_waitcnt lgkmcnt(0)
	v_mfma_f32_16x16x32_bf16 v[124:127], v[154:157], v[190:193], v[124:127]
	v_mfma_f32_16x16x32_bf16 v[120:123], v[162:165], v[190:193], v[120:123]
	v_mfma_f32_16x16x32_bf16 v[108:111], v[154:157], v[198:201], v[108:111]
	v_mfma_f32_16x16x32_bf16 v[104:107], v[162:165], v[198:201], v[104:107]
	v_mfma_f32_16x16x32_bf16 v[92:95], v[154:157], v[206:209], v[92:95]
	v_mfma_f32_16x16x32_bf16 v[88:91], v[162:165], v[206:209], v[88:91]
	v_mfma_f32_16x16x32_bf16 v[76:79], v[154:157], v[214:217], v[76:79]
	v_mfma_f32_16x16x32_bf16 v[72:75], v[162:165], v[214:217], v[72:75]
	v_mfma_f32_16x16x32_bf16 v[124:127], v[158:161], v[194:197], v[124:127]
	v_mfma_f32_16x16x32_bf16 v[120:123], v[166:169], v[194:197], v[120:123]
	v_mfma_f32_16x16x32_bf16 v[108:111], v[158:161], v[202:205], v[108:111]
	v_mfma_f32_16x16x32_bf16 v[104:107], v[166:169], v[202:205], v[104:107]
	v_mfma_f32_16x16x32_bf16 v[92:95], v[158:161], v[210:213], v[92:95]
	v_mfma_f32_16x16x32_bf16 v[88:91], v[166:169], v[210:213], v[88:91]
	v_mfma_f32_16x16x32_bf16 v[76:79], v[158:161], v[218:221], v[76:79]
	v_mfma_f32_16x16x32_bf16 v[72:75], v[166:169], v[218:221], v[72:75]
	v_mfma_f32_16x16x32_bf16 v[116:119], v[170:173], v[190:193], v[116:119]
	v_mfma_f32_16x16x32_bf16 v[112:115], v[178:181], v[190:193], v[112:115]
	v_mfma_f32_16x16x32_bf16 v[100:103], v[170:173], v[198:201], v[100:103]
	v_mfma_f32_16x16x32_bf16 v[96:99], v[178:181], v[198:201], v[96:99]
	v_mfma_f32_16x16x32_bf16 v[84:87], v[170:173], v[206:209], v[84:87]
	v_mfma_f32_16x16x32_bf16 v[80:83], v[178:181], v[206:209], v[80:83]
	v_mfma_f32_16x16x32_bf16 v[68:71], v[170:173], v[214:217], v[68:71]
	v_mfma_f32_16x16x32_bf16 v[64:67], v[178:181], v[214:217], v[64:67]
	v_mfma_f32_16x16x32_bf16 v[116:119], v[174:177], v[194:197], v[116:119]
	v_mfma_f32_16x16x32_bf16 v[112:115], v[182:185], v[194:197], v[112:115]
	v_mfma_f32_16x16x32_bf16 v[100:103], v[174:177], v[202:205], v[100:103]
	v_mfma_f32_16x16x32_bf16 v[96:99], v[182:185], v[202:205], v[96:99]
	v_mfma_f32_16x16x32_bf16 v[84:87], v[174:177], v[210:213], v[84:87]
	v_mfma_f32_16x16x32_bf16 v[80:83], v[182:185], v[210:213], v[80:83]
	v_mfma_f32_16x16x32_bf16 v[68:71], v[174:177], v[218:221], v[68:71]
	v_mfma_f32_16x16x32_bf16 v[64:67], v[182:185], v[218:221], v[64:67]
	s_barrier
	s_add_i32 s75, s38, s24
	v_lshl_add_u64 v[186:187], s[4:5], 0, v[130:131]
	s_mov_b32 m0, s75
	ds_read_b128 v[190:193], v151 offset:16384
	ds_read_b128 v[194:197], v151 offset:17408
	ds_read_b128 v[198:201], v151 offset:18432
	ds_read_b128 v[202:205], v151 offset:19456
	ds_read_b128 v[206:209], v151 offset:20480
	ds_read_b128 v[210:213], v151 offset:21504
	ds_read_b128 v[214:217], v151 offset:22528
	ds_read_b128 v[218:221], v151 offset:23552
	global_load_lds_dwordx4 v[186:187], off
	s_add_i32 m0, s75, 0x2000
	s_add_u32 s78, s4, 0x10000
	v_lshl_add_u64 v[222:223], s[4:5], 0, v[134:135]
	s_addc_u32 s79, s5, 0
	s_add_i32 s75, s39, s24
	global_load_lds_dwordx4 v[222:223], off
	v_lshl_add_u64 v[224:225], s[78:79], 0, v[130:131]
	s_mov_b32 m0, s75
	v_lshl_add_u64 v[226:227], s[22:23], 0, v[132:133]
	global_load_lds_dwordx4 v[224:225], off
	v_lshl_add_u64 v[224:225], s[78:79], 0, v[134:135]
	s_add_i32 m0, s75, 0x2000
	s_nop 0
	global_load_lds_dwordx4 v[224:225], off
	v_lshl_add_u64 v[224:225], s[22:23], 0, v[128:129]
	s_mov_b32 m0, s25
	s_nop 0
	global_load_lds_dwordx4 v[224:225], off
	s_mov_b32 m0, s26
	s_nop 0
	global_load_lds_dwordx4 v[226:227], off
	s_waitcnt vmcnt(8)
	s_waitcnt lgkmcnt(0)
	s_barrier
	s_waitcnt lgkmcnt(0)
	v_mfma_f32_16x16x32_bf16 v[60:63], v[154:157], v[190:193], v[60:63]
	v_mfma_f32_16x16x32_bf16 v[56:59], v[162:165], v[190:193], v[56:59]
	v_mfma_f32_16x16x32_bf16 v[44:47], v[154:157], v[198:201], v[44:47]
	v_mfma_f32_16x16x32_bf16 v[40:43], v[162:165], v[198:201], v[40:43]
	v_mfma_f32_16x16x32_bf16 v[28:31], v[154:157], v[206:209], v[28:31]
	v_mfma_f32_16x16x32_bf16 v[24:27], v[162:165], v[206:209], v[24:27]
	v_mfma_f32_16x16x32_bf16 v[12:15], v[154:157], v[214:217], v[12:15]
	v_mfma_f32_16x16x32_bf16 v[8:11], v[162:165], v[214:217], v[8:11]
	v_mfma_f32_16x16x32_bf16 v[60:63], v[158:161], v[194:197], v[60:63]
	v_mfma_f32_16x16x32_bf16 v[56:59], v[166:169], v[194:197], v[56:59]
	v_mfma_f32_16x16x32_bf16 v[44:47], v[158:161], v[202:205], v[44:47]
	v_mfma_f32_16x16x32_bf16 v[40:43], v[166:169], v[202:205], v[40:43]
	v_mfma_f32_16x16x32_bf16 v[28:31], v[158:161], v[210:213], v[28:31]
	v_mfma_f32_16x16x32_bf16 v[24:27], v[166:169], v[210:213], v[24:27]
	v_mfma_f32_16x16x32_bf16 v[12:15], v[158:161], v[218:221], v[12:15]
	v_mfma_f32_16x16x32_bf16 v[8:11], v[166:169], v[218:221], v[8:11]
	v_mfma_f32_16x16x32_bf16 v[52:55], v[170:173], v[190:193], v[52:55]
	v_mfma_f32_16x16x32_bf16 v[48:51], v[178:181], v[190:193], v[48:51]
	v_mfma_f32_16x16x32_bf16 v[36:39], v[170:173], v[198:201], v[36:39]
	v_mfma_f32_16x16x32_bf16 v[32:35], v[178:181], v[198:201], v[32:35]
	v_mfma_f32_16x16x32_bf16 v[20:23], v[170:173], v[206:209], v[20:23]
	v_mfma_f32_16x16x32_bf16 v[16:19], v[178:181], v[206:209], v[16:19]
	v_mfma_f32_16x16x32_bf16 v[4:7], v[170:173], v[214:217], v[4:7]
	v_mfma_f32_16x16x32_bf16 v[0:3], v[178:181], v[214:217], v[0:3]
	v_mfma_f32_16x16x32_bf16 v[52:55], v[174:177], v[194:197], v[52:55]
	v_mfma_f32_16x16x32_bf16 v[48:51], v[182:185], v[194:197], v[48:51]
	v_mfma_f32_16x16x32_bf16 v[36:39], v[174:177], v[202:205], v[36:39]
	v_mfma_f32_16x16x32_bf16 v[32:35], v[182:185], v[202:205], v[32:35]
	v_mfma_f32_16x16x32_bf16 v[20:23], v[174:177], v[210:213], v[20:23]
	v_mfma_f32_16x16x32_bf16 v[16:19], v[182:185], v[210:213], v[16:19]
	v_mfma_f32_16x16x32_bf16 v[4:7], v[174:177], v[218:221], v[4:7]
	v_mfma_f32_16x16x32_bf16 v[0:3], v[182:185], v[218:221], v[0:3]
	s_barrier
	s_add_i32 s75, 0, 0x18000
	s_add_i32 s78, 0, 0x1c000
	v_add_u32_e32 v166, s75, v146
	v_add_u32_e32 v182, s78, v146
	ds_read_b128 v[154:157], v166
	ds_read_b128 v[158:161], v166 offset:1024
	ds_read_b128 v[162:165], v166 offset:2048
	ds_read_b128 v[166:169], v166 offset:3072
	ds_read_b128 v[170:173], v182
	ds_read_b128 v[174:177], v182 offset:1024
	ds_read_b128 v[178:181], v182 offset:2048
	ds_read_b128 v[182:185], v182 offset:3072
	s_add_u32 s22, s22, 0x304000
	s_addc_u32 s23, s23, 0
	s_mov_b32 m0, s27
	v_lshl_add_u64 v[228:229], s[22:23], 0, v[128:129]
	ds_read_b128 v[190:193], v151 offset:32768
	ds_read_b128 v[194:197], v151 offset:33792
	ds_read_b128 v[198:201], v151 offset:34816
	ds_read_b128 v[202:205], v151 offset:35840
	ds_read_b128 v[206:209], v151 offset:36864
	ds_read_b128 v[210:213], v151 offset:37888
	ds_read_b128 v[214:217], v151 offset:38912
	ds_read_b128 v[218:221], v151 offset:39936
	global_load_lds_dwordx4 v[228:229], off
	v_lshl_add_u64 v[228:229], s[22:23], 0, v[132:133]
	s_mov_b32 m0, s35
	s_nop 0
	global_load_lds_dwordx4 v[228:229], off
	s_waitcnt vmcnt(8)
	s_waitcnt lgkmcnt(0)
	s_barrier
	s_waitcnt lgkmcnt(0)
	v_mfma_f32_16x16x32_bf16 v[124:127], v[154:157], v[190:193], v[124:127]
	v_mfma_f32_16x16x32_bf16 v[120:123], v[162:165], v[190:193], v[120:123]
	v_mfma_f32_16x16x32_bf16 v[108:111], v[154:157], v[198:201], v[108:111]
	v_mfma_f32_16x16x32_bf16 v[104:107], v[162:165], v[198:201], v[104:107]
	v_mfma_f32_16x16x32_bf16 v[92:95], v[154:157], v[206:209], v[92:95]
	v_mfma_f32_16x16x32_bf16 v[88:91], v[162:165], v[206:209], v[88:91]
	v_mfma_f32_16x16x32_bf16 v[76:79], v[154:157], v[214:217], v[76:79]
	v_mfma_f32_16x16x32_bf16 v[72:75], v[162:165], v[214:217], v[72:75]
	v_mfma_f32_16x16x32_bf16 v[124:127], v[158:161], v[194:197], v[124:127]
	v_mfma_f32_16x16x32_bf16 v[120:123], v[166:169], v[194:197], v[120:123]
	v_mfma_f32_16x16x32_bf16 v[108:111], v[158:161], v[202:205], v[108:111]
	v_mfma_f32_16x16x32_bf16 v[104:107], v[166:169], v[202:205], v[104:107]
	v_mfma_f32_16x16x32_bf16 v[92:95], v[158:161], v[210:213], v[92:95]
	v_mfma_f32_16x16x32_bf16 v[88:91], v[166:169], v[210:213], v[88:91]
	v_mfma_f32_16x16x32_bf16 v[76:79], v[158:161], v[218:221], v[76:79]
	v_mfma_f32_16x16x32_bf16 v[72:75], v[166:169], v[218:221], v[72:75]
	v_mfma_f32_16x16x32_bf16 v[116:119], v[170:173], v[190:193], v[116:119]
	v_mfma_f32_16x16x32_bf16 v[112:115], v[178:181], v[190:193], v[112:115]
	v_mfma_f32_16x16x32_bf16 v[100:103], v[170:173], v[198:201], v[100:103]
	v_mfma_f32_16x16x32_bf16 v[96:99], v[178:181], v[198:201], v[96:99]
	v_mfma_f32_16x16x32_bf16 v[84:87], v[170:173], v[206:209], v[84:87]
	v_mfma_f32_16x16x32_bf16 v[80:83], v[178:181], v[206:209], v[80:83]
	v_mfma_f32_16x16x32_bf16 v[68:71], v[170:173], v[214:217], v[68:71]
	v_mfma_f32_16x16x32_bf16 v[64:67], v[178:181], v[214:217], v[64:67]
	v_mfma_f32_16x16x32_bf16 v[116:119], v[174:177], v[194:197], v[116:119]
	v_mfma_f32_16x16x32_bf16 v[112:115], v[182:185], v[194:197], v[112:115]
	v_mfma_f32_16x16x32_bf16 v[100:103], v[174:177], v[202:205], v[100:103]
	v_mfma_f32_16x16x32_bf16 v[96:99], v[182:185], v[202:205], v[96:99]
	v_mfma_f32_16x16x32_bf16 v[84:87], v[174:177], v[210:213], v[84:87]
	v_mfma_f32_16x16x32_bf16 v[80:83], v[182:185], v[210:213], v[80:83]
	v_mfma_f32_16x16x32_bf16 v[68:71], v[174:177], v[218:221], v[68:71]
	v_mfma_f32_16x16x32_bf16 v[64:67], v[182:185], v[218:221], v[64:67]
	s_barrier
	s_add_i32 s22, s75, s24
	v_lshl_add_u64 v[186:187], v[186:187], 0, s[8:9]
	s_mov_b32 m0, s22
	ds_read_b128 v[190:193], v151 offset:49152
	ds_read_b128 v[194:197], v151 offset:50176
	ds_read_b128 v[198:201], v151 offset:51200
	ds_read_b128 v[202:205], v151 offset:52224
	ds_read_b128 v[206:209], v151 offset:53248
	ds_read_b128 v[210:213], v151 offset:54272
	ds_read_b128 v[214:217], v151 offset:55296
	ds_read_b128 v[218:221], v151 offset:56320
	global_load_lds_dwordx4 v[186:187], off
	s_add_i32 m0, s22, 0x2000
	s_add_u32 s4, s4, 0x10080
	v_lshl_add_u64 v[186:187], v[222:223], 0, s[8:9]
	s_addc_u32 s5, s5, 0
	s_add_i32 s22, s78, s24
	global_load_lds_dwordx4 v[186:187], off
	v_lshl_add_u64 v[186:187], s[4:5], 0, v[130:131]
	s_mov_b32 m0, s22
	s_nop 0
	global_load_lds_dwordx4 v[186:187], off
	v_lshl_add_u64 v[186:187], s[4:5], 0, v[134:135]
	s_add_i32 m0, s22, 0x2000
	s_nop 0
	global_load_lds_dwordx4 v[186:187], off
	v_lshl_add_u64 v[186:187], v[224:225], 0, s[8:9]
	s_mov_b32 m0, s36
	s_nop 0
	global_load_lds_dwordx4 v[186:187], off
	v_lshl_add_u64 v[186:187], v[226:227], 0, s[8:9]
	s_mov_b32 m0, s37
	s_nop 0
	global_load_lds_dwordx4 v[186:187], off
	s_waitcnt vmcnt(8)
	s_waitcnt lgkmcnt(0)
	s_barrier
	s_waitcnt lgkmcnt(0)
	v_mfma_f32_16x16x32_bf16 v[60:63], v[154:157], v[190:193], v[60:63]
	v_mfma_f32_16x16x32_bf16 v[56:59], v[162:165], v[190:193], v[56:59]
	v_mfma_f32_16x16x32_bf16 v[44:47], v[154:157], v[198:201], v[44:47]
	v_mfma_f32_16x16x32_bf16 v[40:43], v[162:165], v[198:201], v[40:43]
	v_mfma_f32_16x16x32_bf16 v[28:31], v[154:157], v[206:209], v[28:31]
	v_mfma_f32_16x16x32_bf16 v[24:27], v[162:165], v[206:209], v[24:27]
	v_mfma_f32_16x16x32_bf16 v[12:15], v[154:157], v[214:217], v[12:15]
	v_mfma_f32_16x16x32_bf16 v[8:11], v[162:165], v[214:217], v[8:11]
	v_mfma_f32_16x16x32_bf16 v[60:63], v[158:161], v[194:197], v[60:63]
	v_mfma_f32_16x16x32_bf16 v[56:59], v[166:169], v[194:197], v[56:59]
	v_mfma_f32_16x16x32_bf16 v[44:47], v[158:161], v[202:205], v[44:47]
	v_mfma_f32_16x16x32_bf16 v[40:43], v[166:169], v[202:205], v[40:43]
	v_mfma_f32_16x16x32_bf16 v[28:31], v[158:161], v[210:213], v[28:31]
	v_mfma_f32_16x16x32_bf16 v[24:27], v[166:169], v[210:213], v[24:27]
	v_mfma_f32_16x16x32_bf16 v[12:15], v[158:161], v[218:221], v[12:15]
	v_mfma_f32_16x16x32_bf16 v[8:11], v[166:169], v[218:221], v[8:11]
	v_mfma_f32_16x16x32_bf16 v[52:55], v[170:173], v[190:193], v[52:55]
	v_mfma_f32_16x16x32_bf16 v[48:51], v[178:181], v[190:193], v[48:51]
	v_mfma_f32_16x16x32_bf16 v[36:39], v[170:173], v[198:201], v[36:39]
	v_mfma_f32_16x16x32_bf16 v[32:35], v[178:181], v[198:201], v[32:35]
	v_mfma_f32_16x16x32_bf16 v[20:23], v[170:173], v[206:209], v[20:23]
	v_mfma_f32_16x16x32_bf16 v[16:19], v[178:181], v[206:209], v[16:19]
	v_mfma_f32_16x16x32_bf16 v[4:7], v[170:173], v[214:217], v[4:7]
	v_mfma_f32_16x16x32_bf16 v[0:3], v[178:181], v[214:217], v[0:3]
	v_mfma_f32_16x16x32_bf16 v[52:55], v[174:177], v[194:197], v[52:55]
	v_mfma_f32_16x16x32_bf16 v[48:51], v[182:185], v[194:197], v[48:51]
	v_mfma_f32_16x16x32_bf16 v[36:39], v[174:177], v[202:205], v[36:39]
	v_mfma_f32_16x16x32_bf16 v[32:35], v[182:185], v[202:205], v[32:35]
	v_mfma_f32_16x16x32_bf16 v[20:23], v[174:177], v[210:213], v[20:23]
	v_mfma_f32_16x16x32_bf16 v[16:19], v[182:185], v[210:213], v[16:19]
	v_mfma_f32_16x16x32_bf16 v[4:7], v[174:177], v[218:221], v[4:7]
	v_mfma_f32_16x16x32_bf16 v[0:3], v[182:185], v[218:221], v[0:3]
	s_barrier
	s_add_i32 s4, s73, 4
	s_and_b32 s4, s4, 6
	s_cmp_lg_u32 s4, 0
	s_cbranch_scc1 .LBB0_895
	v_add_u32_e32 v154, s74, v148
	v_add_u32_e32 v155, 0x26500, v154
	v_add_u32_e32 v156, 0x26540, v154
	v_add_u32_e32 v157, 0x26580, v154
	v_add_u32_e32 v159, 0x265c0, v154
	v_add_u32_e32 v161, 0x26700, v154
	v_add_u32_e32 v163, 0x26740, v154
	v_add_u32_e32 v165, 0x26780, v154
	v_add_u32_e32 v167, 0x267c0, v154
	ds_read_b32 v154, v155
	ds_read_b32 v156, v156
	ds_read_b32 v158, v157
	ds_read_b32 v160, v159
	ds_read_b32 v162, v161
	ds_read_b32 v164, v163
	ds_read_b32 v166, v165
	ds_read_b32 v168, v167
	s_waitcnt lgkmcnt(0)
	v_pk_mul_f32 v[126:127], v[126:127], v[154:155] op_sel_hi:[1,0]
	v_pk_mul_f32 v[124:125], v[124:125], v[154:155] op_sel_hi:[1,0]
	v_pk_mul_f32 v[122:123], v[122:123], v[154:155] op_sel_hi:[1,0]
	v_pk_mul_f32 v[120:121], v[120:121], v[154:155] op_sel_hi:[1,0]
	v_pk_mul_f32 v[118:119], v[118:119], v[154:155] op_sel_hi:[1,0]
	v_pk_mul_f32 v[116:117], v[116:117], v[154:155] op_sel_hi:[1,0]
	v_pk_mul_f32 v[114:115], v[114:115], v[154:155] op_sel_hi:[1,0]
	v_pk_mul_f32 v[112:113], v[112:113], v[154:155] op_sel_hi:[1,0]
	v_pk_mul_f32 v[110:111], v[110:111], v[156:157] op_sel_hi:[1,0]
	v_pk_mul_f32 v[108:109], v[108:109], v[156:157] op_sel_hi:[1,0]
	v_pk_mul_f32 v[106:107], v[106:107], v[156:157] op_sel_hi:[1,0]
	v_pk_mul_f32 v[104:105], v[104:105], v[156:157] op_sel_hi:[1,0]
	v_pk_mul_f32 v[102:103], v[102:103], v[156:157] op_sel_hi:[1,0]
	v_pk_mul_f32 v[100:101], v[100:101], v[156:157] op_sel_hi:[1,0]
	v_pk_mul_f32 v[98:99], v[98:99], v[156:157] op_sel_hi:[1,0]
	v_pk_mul_f32 v[96:97], v[96:97], v[156:157] op_sel_hi:[1,0]
	v_pk_mul_f32 v[94:95], v[94:95], v[158:159] op_sel_hi:[1,0]
	v_pk_mul_f32 v[92:93], v[92:93], v[158:159] op_sel_hi:[1,0]
	v_pk_mul_f32 v[90:91], v[90:91], v[158:159] op_sel_hi:[1,0]
	v_pk_mul_f32 v[88:89], v[88:89], v[158:159] op_sel_hi:[1,0]
	v_pk_mul_f32 v[86:87], v[86:87], v[158:159] op_sel_hi:[1,0]
	v_pk_mul_f32 v[84:85], v[84:85], v[158:159] op_sel_hi:[1,0]
	v_pk_mul_f32 v[82:83], v[82:83], v[158:159] op_sel_hi:[1,0]
	v_pk_mul_f32 v[80:81], v[80:81], v[158:159] op_sel_hi:[1,0]
	v_pk_mul_f32 v[78:79], v[78:79], v[160:161] op_sel_hi:[1,0]
	v_pk_mul_f32 v[76:77], v[76:77], v[160:161] op_sel_hi:[1,0]
	v_pk_mul_f32 v[74:75], v[74:75], v[160:161] op_sel_hi:[1,0]
	v_pk_mul_f32 v[72:73], v[72:73], v[160:161] op_sel_hi:[1,0]
	v_pk_mul_f32 v[70:71], v[70:71], v[160:161] op_sel_hi:[1,0]
	v_pk_mul_f32 v[68:69], v[68:69], v[160:161] op_sel_hi:[1,0]
	v_pk_mul_f32 v[66:67], v[66:67], v[160:161] op_sel_hi:[1,0]
	v_pk_mul_f32 v[64:65], v[64:65], v[160:161] op_sel_hi:[1,0]
	v_pk_mul_f32 v[62:63], v[62:63], v[162:163] op_sel_hi:[1,0]
	v_pk_mul_f32 v[60:61], v[60:61], v[162:163] op_sel_hi:[1,0]
	v_pk_mul_f32 v[58:59], v[58:59], v[162:163] op_sel_hi:[1,0]
	v_pk_mul_f32 v[56:57], v[56:57], v[162:163] op_sel_hi:[1,0]
	v_pk_mul_f32 v[54:55], v[54:55], v[162:163] op_sel_hi:[1,0]
	v_pk_mul_f32 v[52:53], v[52:53], v[162:163] op_sel_hi:[1,0]
	v_pk_mul_f32 v[50:51], v[50:51], v[162:163] op_sel_hi:[1,0]
	v_pk_mul_f32 v[48:49], v[48:49], v[162:163] op_sel_hi:[1,0]
	v_pk_mul_f32 v[46:47], v[46:47], v[164:165] op_sel_hi:[1,0]
	v_pk_mul_f32 v[44:45], v[44:45], v[164:165] op_sel_hi:[1,0]
	v_pk_mul_f32 v[42:43], v[42:43], v[164:165] op_sel_hi:[1,0]
	v_pk_mul_f32 v[40:41], v[40:41], v[164:165] op_sel_hi:[1,0]
	v_pk_mul_f32 v[38:39], v[38:39], v[164:165] op_sel_hi:[1,0]
	v_pk_mul_f32 v[36:37], v[36:37], v[164:165] op_sel_hi:[1,0]
	v_pk_mul_f32 v[34:35], v[34:35], v[164:165] op_sel_hi:[1,0]
	v_pk_mul_f32 v[32:33], v[32:33], v[164:165] op_sel_hi:[1,0]
	v_pk_mul_f32 v[30:31], v[30:31], v[166:167] op_sel_hi:[1,0]
	v_pk_mul_f32 v[28:29], v[28:29], v[166:167] op_sel_hi:[1,0]
	v_pk_mul_f32 v[26:27], v[26:27], v[166:167] op_sel_hi:[1,0]
	v_pk_mul_f32 v[24:25], v[24:25], v[166:167] op_sel_hi:[1,0]
	v_pk_mul_f32 v[22:23], v[22:23], v[166:167] op_sel_hi:[1,0]
	v_pk_mul_f32 v[20:21], v[20:21], v[166:167] op_sel_hi:[1,0]
	v_pk_mul_f32 v[18:19], v[18:19], v[166:167] op_sel_hi:[1,0]
	v_pk_mul_f32 v[16:17], v[16:17], v[166:167] op_sel_hi:[1,0]
	v_pk_mul_f32 v[14:15], v[14:15], v[168:169] op_sel_hi:[1,0]
	v_pk_mul_f32 v[12:13], v[12:13], v[168:169] op_sel_hi:[1,0]
	v_pk_mul_f32 v[10:11], v[10:11], v[168:169] op_sel_hi:[1,0]
	v_pk_mul_f32 v[8:9], v[8:9], v[168:169] op_sel_hi:[1,0]
	v_pk_mul_f32 v[6:7], v[6:7], v[168:169] op_sel_hi:[1,0]
	v_pk_mul_f32 v[4:5], v[4:5], v[168:169] op_sel_hi:[1,0]
	v_pk_mul_f32 v[2:3], v[2:3], v[168:169] op_sel_hi:[1,0]
	v_pk_mul_f32 v[0:1], v[0:1], v[168:169] op_sel_hi:[1,0]
	s_branch .LBB0_895
